# sparse attention phase rewritten by hand (one-shot softmax, 8-key dwordx4 V gather, batched LDS broadcast) + head-major fp8 K/V copies
# speedup vs baseline: 1.2471x; 1.2471x over previous
; __device__ __forceinline__ void sparse_unit7(const bf16_t* QKV, const unsigned char* K8, const unsigned char* V8, const int (&selv)[4], bf16_t* OB, LAS unsigned char* wl, int t, int h, int lane) {
;     LAS int* wsel = (LAS int*)wl; LAS unsigned* otw = (LAS unsigned*)(wl + 1024); LAS float* ptw = (LAS float*)(wl + 2048);
;     const int n16 = lane & 15, slab = lane >> 4, half = lane >> 5, l4 = (lane & 31) * 4;
;     const bf16_t* qrow = QKV + (size_t)t * QKVW + COL_BQ + h * 128 + 16 * slab;
;     long qa[4];
; #pragma unroll
;     for (int ks = 0; ks < 4; ++ks) { const u32x4 raw = *(const u32x4*)(qrow + 8 * (ks & 1) + 64 * (ks >> 1)); const unsigned w[4] = {raw.x, raw.y, raw.z, raw.w}; float x[8];
; #pragma unroll
;         for (int i = 0; i < 4; ++i) { x[2 * i] = bf2f(w[i] & 0xffffu); x[2 * i + 1] = __builtin_bit_cast(float, w[i] & 0xffff0000u); }
;         const u32x2 f = to_fp8x8(x); qa[ks] = (long)(((unsigned long long)f.y << 32) | f.x); }
;     const unsigned char* K8h = K8 + h * 128; const unsigned char* V8h = V8 + h * 128;
;     const int n = min(256, t + 1), ns = (n + 63) >> 6;
; #pragma unroll
;     for (int s = 0; s < 4; ++s) { const int j = 64 * s + lane; const int id = (j < n) ? selv[s] : 0; wsel[j] = id; otw[j] = (unsigned)id * 1024u; }
;     asm volatile("" ::: "memory");
;     long kf[16]; unsigned va[8], vb[8];
;     s8_issue_k(kf, K8h, wsel, 0, n16, slab);
; __global__ void __launch_bounds__(NTHREADS, 2) mega(Args a) {
;     ...
;                 const int h = blockIdx.x & 7, qg = (blockIdx.x >> 3) * NWAVES + wave, nqg = ((G + 7) >> 3) * NWAVES;
;                 for (int u = gw; u < SEQ * 4; u += NGW) dilated_merge(OG, LSE, OA, u >> 2, u & 3, lane);
;                 for (int rep = 0; rep < REP_SP; ++rep)
;                 if ((G & 7) == 0) { int seln[4];
; #pragma unroll
;                     for (int s = 0; s < 4; ++s) seln[s] = (int)SEL[(size_t)min(qg, SEQ - 1) * 256 + 64 * s + lane];
;                     for (int t = qg; t < SEQ; t += nqg) { int selc[4];
; #pragma unroll
;                         for (int s = 0; s < 4; ++s) selc[s] = seln[s];
;                         const int tn = min(t + nqg, SEQ - 1);
; #pragma unroll
;                         for (int s = 0; s < 4; ++s) seln[s] = (int)SEL[(size_t)tn * 256 + 64 * s + lane];
;                         sparse_unit7(QKV, K8, V8, selc, OB, lds + wave * 4096, t, h, lane); } }
.LBB0_160:
.LBB0_161:
	v_readlane_b32 s0, v251, 0
	v_readlane_b32 s1, v250, 18
	s_nop 3
	s_and_b32 s4, s0, 7
	s_and_b32 s5, s0, -8
	s_add_i32 s34, s5, s1
	s_add_i32 s48, s94, 7
	s_and_b32 s48, s48, -8
	s_add_u32 s38, s90, 0x28600000
	s_addc_u32 s39, s91, 0
	s_lshl_b32 s5, s4, 8
	s_add_u32 s5, s5, 0x12302400
	s_add_u32 s40, s90, s5
	s_addc_u32 s41, s91, 0
	s_lshl_b32 s5, s4, 21
	s_add_u32 s0, s5, 0x3cf00000
	s_add_u32 s42, s90, s0
	s_addc_u32 s43, s91, 0
	s_add_u32 s0, s5, 0x3df00000
	s_add_u32 s44, s90, s0
	s_addc_u32 s45, s91, 0
	s_lshl_b32 s5, s4, 8
	s_add_u32 s0, s5, 0x29e00000
	s_add_u32 s46, s90, s0
	s_addc_u32 s47, s91, 0
	v_and_b32_e32 v218, 15, v182
	v_lshrrev_b32_e32 v219, 4, v182
	v_and_b32_e32 v246, 7, v182
	v_lshrrev_b32_e32 v247, 3, v182
	v_lshlrev_b32_e32 v200, 5, v218
	v_lshlrev_b32_e32 v201, 5, v219
	v_lshlrev_b32_e32 v202, 4, v219
	v_lshlrev_b32_e32 v203, 4, v246
	v_lshlrev_b32_e32 v217, 4, v218
	v_lshl_add_u32 v217, v219, 2, v217
	v_lshlrev_b32_e32 v216, 1, v217
	v_lshrrev_b32_e32 v248, 1, v218
	v_lshl_add_u32 v248, v248, 2, v217
	v_lshlrev_b32_e32 v213, 2, v248
	s_lshl_b32 s0, s1, 12
	v_add_u32_e32 v213, s0, v213
	v_mul_u32_u24_e32 v214, 0x90, v247
	v_add_u32_e32 v214, s0, v214
	v_lshlrev_b32_e32 v215, 5, v246
	v_lshl_add_u32 v215, v219, 3, v215
	v_cmp_eq_u32_e64 s[8:9], 0, v219
	v_cmp_eq_u32_e64 s[10:11], 1, v219
	v_cmp_eq_u32_e64 s[16:17], 2, v219
	v_cmp_eq_u32_e64 s[22:23], 3, v219
	s_lshl_b32 s0, s34, 9
	s_add_u32 s0, s38, s0
	s_addc_u32 s1, s39, 0
	s_mul_i32 s4, s34, 0x3c00
	s_add_u32 s4, s40, s4
	s_addc_u32 s5, s41, 0
	global_load_dwordx4 v[220:223], v200, s[0:1]
	global_load_dwordx4 v[224:227], v200, s[0:1] offset:16
	global_load_dwordx2 v[228:229], v216, s[0:1]
	global_load_dwordx4 v[230:233], v201, s[4:5]
	global_load_dwordx4 v[234:237], v201, s[4:5] offset:16
	global_load_dwordx4 v[238:241], v201, s[4:5] offset:128
	global_load_dwordx4 v[242:245], v201, s[4:5] offset:144
.Lsp_unit:
	s_waitcnt vmcnt(0)
	s_add_i32 s98, s34, 1
	s_min_i32 s98, s98, 0x100
	v_and_b32_e32 v218, 0x3fff, v220
	v_lshl_add_u32 v218, v218, 7, v202
	global_load_dwordx4 v[0:3], v218, s[42:43]
	global_load_dwordx4 v[4:7], v218, s[42:43] offset:64
	v_bfe_u32 v218, v220, 16, 14
	v_lshl_add_u32 v218, v218, 7, v202
	global_load_dwordx4 v[8:11], v218, s[42:43]
	global_load_dwordx4 v[12:15], v218, s[42:43] offset:64
	v_and_b32_e32 v218, 0x3fff, v221
	v_lshl_add_u32 v218, v218, 7, v202
	global_load_dwordx4 v[16:19], v218, s[42:43]
	global_load_dwordx4 v[20:23], v218, s[42:43] offset:64
	v_bfe_u32 v218, v221, 16, 14
	v_lshl_add_u32 v218, v218, 7, v202
	global_load_dwordx4 v[24:27], v218, s[42:43]
	global_load_dwordx4 v[28:31], v218, s[42:43] offset:64
	v_and_b32_e32 v218, 0x3fff, v222
	v_lshl_add_u32 v218, v218, 7, v202
	global_load_dwordx4 v[32:35], v218, s[42:43]
	global_load_dwordx4 v[36:39], v218, s[42:43] offset:64
	v_bfe_u32 v218, v222, 16, 14
	v_lshl_add_u32 v218, v218, 7, v202
	global_load_dwordx4 v[40:43], v218, s[42:43]
	global_load_dwordx4 v[44:47], v218, s[42:43] offset:64
	v_and_b32_e32 v218, 0x3fff, v223
	v_lshl_add_u32 v218, v218, 7, v202
	global_load_dwordx4 v[48:51], v218, s[42:43]
	global_load_dwordx4 v[52:55], v218, s[42:43] offset:64
	v_bfe_u32 v218, v223, 16, 14
	v_lshl_add_u32 v218, v218, 7, v202
	global_load_dwordx4 v[56:59], v218, s[42:43]
	global_load_dwordx4 v[60:63], v218, s[42:43] offset:64
	v_and_b32_e32 v218, 0x3fff, v224
	v_lshl_add_u32 v218, v218, 7, v202
	global_load_dwordx4 v[64:67], v218, s[42:43]
	global_load_dwordx4 v[68:71], v218, s[42:43] offset:64
	v_bfe_u32 v218, v224, 16, 14
	v_lshl_add_u32 v218, v218, 7, v202
	global_load_dwordx4 v[72:75], v218, s[42:43]
	global_load_dwordx4 v[76:79], v218, s[42:43] offset:64
	v_and_b32_e32 v218, 0x3fff, v225
	v_lshl_add_u32 v218, v218, 7, v202
	global_load_dwordx4 v[80:83], v218, s[42:43]
	global_load_dwordx4 v[84:87], v218, s[42:43] offset:64
	v_bfe_u32 v218, v225, 16, 14
	v_lshl_add_u32 v218, v218, 7, v202
	global_load_dwordx4 v[88:91], v218, s[42:43]
	global_load_dwordx4 v[92:95], v218, s[42:43] offset:64
	v_and_b32_e32 v218, 0x3fff, v226
	v_lshl_add_u32 v218, v218, 7, v202
	global_load_dwordx4 v[96:99], v218, s[42:43]
	global_load_dwordx4 v[100:103], v218, s[42:43] offset:64
	v_bfe_u32 v218, v226, 16, 14
	v_lshl_add_u32 v218, v218, 7, v202
	global_load_dwordx4 v[104:107], v218, s[42:43]
	global_load_dwordx4 v[108:111], v218, s[42:43] offset:64
	v_and_b32_e32 v218, 0x3fff, v227
	v_lshl_add_u32 v218, v218, 7, v202
	global_load_dwordx4 v[112:115], v218, s[42:43]
	global_load_dwordx4 v[116:119], v218, s[42:43] offset:64
	v_bfe_u32 v218, v227, 16, 14
	v_lshl_add_u32 v218, v218, 7, v202
	global_load_dwordx4 v[120:123], v218, s[42:43]
	global_load_dwordx4 v[124:127], v218, s[42:43] offset:64
	v_and_b32_e32 v136, 0x3fff, v228
	v_bfe_u32 v137, v228, 16, 14
	v_and_b32_e32 v138, 0x3fff, v229
	v_bfe_u32 v139, v229, 16, 14
	v_lshlrev_b32_e32 v136, 7, v136
	v_lshlrev_b32_e32 v137, 7, v137
	v_lshlrev_b32_e32 v138, 7, v138
	v_lshlrev_b32_e32 v139, 7, v139
	v_lshlrev_b32_e32 v218, 16, v230
	v_and_b32_e32 v219, 0xffff0000, v230
	v_lshlrev_b32_e32 v246, 16, v231
	v_and_b32_e32 v247, 0xffff0000, v231
	v_cvt_pk_fp8_f32 v128, v218, v219
	s_nop 0
	v_cvt_pk_fp8_f32 v128, v246, v247 op_sel:[0,0,1]
	v_lshlrev_b32_e32 v218, 16, v232
	v_and_b32_e32 v219, 0xffff0000, v232
	v_lshlrev_b32_e32 v246, 16, v233
	v_and_b32_e32 v247, 0xffff0000, v233
	v_cvt_pk_fp8_f32 v129, v218, v219
	s_nop 0
	v_cvt_pk_fp8_f32 v129, v246, v247 op_sel:[0,0,1]
	v_lshlrev_b32_e32 v218, 16, v234
	v_and_b32_e32 v219, 0xffff0000, v234
	v_lshlrev_b32_e32 v246, 16, v235
	v_and_b32_e32 v247, 0xffff0000, v235
; #define LAS __attribute__((address_space(3)))
; __device__ __forceinline__ void sparse_unit7(const bf16_t* QKV, const unsigned char* K8, const unsigned char* V8, const int (&selv)[4], bf16_t* OB, LAS unsigned char* wl, int t, int h, int lane) {
;     ...
;     for (int ks = 0; ks < 4; ++ks) { const u32x4 raw = *(const u32x4*)(qrow + 8 * (ks & 1) + 64 * (ks >> 1)); const unsigned w[4] = {raw.x, raw.y, raw.z, raw.w}; float x[8];
; #pragma unroll
;         for (int i = 0; i < 4; ++i) { x[2 * i] = bf2f(w[i] & 0xffffu); x[2 * i + 1] = __builtin_bit_cast(float, w[i] & 0xffff0000u); }
;         const u32x2 f = to_fp8x8(x); qa[ks] = (long)(((unsigned long long)f.y << 32) | f.x); }
;     const unsigned char* K8h = K8 + h * 128; const unsigned char* V8h = V8 + h * 128;
;     const int n = min(256, t + 1), ns = (n + 63) >> 6;
; #pragma unroll
;     for (int s = 0; s < 4; ++s) { const int j = 64 * s + lane; const int id = (j < n) ? selv[s] : 0; wsel[j] = id; otw[j] = (unsigned)id * 1024u; }
;     asm volatile("" ::: "memory");
;     long kf[16]; unsigned va[8], vb[8];
;     s8_issue_k(kf, K8h, wsel, 0, n16, slab);
;     s9_issue_v<0>(va, V8h, otw, half, l4);
;     float m = -INFINITY, l = 0.f; f32x2_t oa = {0.f, 0.f}, ob = {0.f, 0.f};
; #pragma unroll
;     for (int s = 0; s < 4; ++s) {
;         if (s < ns) {
;             const bool valid = (64 * s + lane) < n;
;             LAS const unsigned* ot = otw + 64 * s; LAS float* pt = ptw + 64 * s;
;             s9_issue_v<1>(vb, V8h, ot, half, l4);
;             f32x4 acc[4];
; #pragma unroll
;             for (int g = 0; g < 4; ++g) { acc[g] = (f32x4){0.f, 0.f, 0.f, 0.f};
; #pragma unroll
;                 for (int ks = 0; ks < 4; ++ks) acc[g] = __builtin_amdgcn_mfma_f32_16x16x32_fp8_fp8(qa[ks], kf[g * 4 + ks], acc[g], 0, 0, 0); }
;             float sc = (slab == 0) ? acc[0][0] : (slab == 1) ? acc[1][0] : (slab == 2) ? acc[2][0] : acc[3][0];
	v_cvt_pk_fp8_f32 v130, v218, v219
	s_nop 0
	v_cvt_pk_fp8_f32 v130, v246, v247 op_sel:[0,0,1]
	v_lshlrev_b32_e32 v218, 16, v236
	v_and_b32_e32 v219, 0xffff0000, v236
	v_lshlrev_b32_e32 v246, 16, v237
	v_and_b32_e32 v247, 0xffff0000, v237
	v_cvt_pk_fp8_f32 v131, v218, v219
	s_nop 0
	v_cvt_pk_fp8_f32 v131, v246, v247 op_sel:[0,0,1]
	v_lshlrev_b32_e32 v218, 16, v238
	v_and_b32_e32 v219, 0xffff0000, v238
	v_lshlrev_b32_e32 v246, 16, v239
	v_and_b32_e32 v247, 0xffff0000, v239
	v_cvt_pk_fp8_f32 v132, v218, v219
	s_nop 0
	v_cvt_pk_fp8_f32 v132, v246, v247 op_sel:[0,0,1]
	v_lshlrev_b32_e32 v218, 16, v240
	v_and_b32_e32 v219, 0xffff0000, v240
	v_lshlrev_b32_e32 v246, 16, v241
	v_and_b32_e32 v247, 0xffff0000, v241
	v_cvt_pk_fp8_f32 v133, v218, v219
	s_nop 0
	v_cvt_pk_fp8_f32 v133, v246, v247 op_sel:[0,0,1]
	v_lshlrev_b32_e32 v218, 16, v242
	v_and_b32_e32 v219, 0xffff0000, v242
	v_lshlrev_b32_e32 v246, 16, v243
	v_and_b32_e32 v247, 0xffff0000, v243
	v_cvt_pk_fp8_f32 v134, v218, v219
	s_nop 0
	v_cvt_pk_fp8_f32 v134, v246, v247 op_sel:[0,0,1]
	v_lshlrev_b32_e32 v218, 16, v244
	v_and_b32_e32 v219, 0xffff0000, v244
	v_lshlrev_b32_e32 v246, 16, v245
	v_and_b32_e32 v247, 0xffff0000, v245
	v_cvt_pk_fp8_f32 v135, v218, v219
	s_nop 0
	v_cvt_pk_fp8_f32 v135, v246, v247 op_sel:[0,0,1]
	s_add_i32 s49, s34, s48
	s_min_i32 s49, s49, 0x3fff
	s_lshl_b32 s0, s49, 9
	s_add_u32 s0, s38, s0
	s_addc_u32 s1, s39, 0
	s_mul_i32 s4, s49, 0x3c00
	s_add_u32 s4, s40, s4
	s_addc_u32 s5, s41, 0
	global_load_dwordx4 v[220:223], v200, s[0:1]
	global_load_dwordx4 v[224:227], v200, s[0:1] offset:16
	global_load_dwordx2 v[228:229], v216, s[0:1]
	global_load_dwordx4 v[230:233], v201, s[4:5]
	global_load_dwordx4 v[234:237], v201, s[4:5] offset:16
	global_load_dwordx4 v[238:241], v201, s[4:5] offset:128
	global_load_dwordx4 v[242:245], v201, s[4:5] offset:144
	s_waitcnt vmcnt(37)
	v_mfma_f32_16x16x32_fp8_fp8 v[184:187], v[128:129], v[0:1], 0
	v_mfma_f32_16x16x32_fp8_fp8 v[184:187], v[130:131], v[2:3], v[184:187]
	v_mfma_f32_16x16x32_fp8_fp8 v[184:187], v[132:133], v[4:5], v[184:187]
	v_mfma_f32_16x16x32_fp8_fp8 v[184:187], v[134:135], v[6:7], v[184:187]
	s_waitcnt vmcnt(35)
	v_mfma_f32_16x16x32_fp8_fp8 v[188:191], v[128:129], v[8:9], 0
	v_mfma_f32_16x16x32_fp8_fp8 v[188:191], v[130:131], v[10:11], v[188:191]
	v_mfma_f32_16x16x32_fp8_fp8 v[188:191], v[132:133], v[12:13], v[188:191]
	v_mfma_f32_16x16x32_fp8_fp8 v[188:191], v[134:135], v[14:15], v[188:191]
	s_waitcnt vmcnt(33)
	v_mfma_f32_16x16x32_fp8_fp8 v[192:195], v[128:129], v[16:17], 0
	v_mfma_f32_16x16x32_fp8_fp8 v[192:195], v[130:131], v[18:19], v[192:195]
	v_mfma_f32_16x16x32_fp8_fp8 v[192:195], v[132:133], v[20:21], v[192:195]
	v_mfma_f32_16x16x32_fp8_fp8 v[192:195], v[134:135], v[22:23], v[192:195]
	v_cndmask_b32_e64 v140, v140, v184, s[8:9]
	s_waitcnt vmcnt(31)
	v_mfma_f32_16x16x32_fp8_fp8 v[196:199], v[128:129], v[24:25], 0
	v_mfma_f32_16x16x32_fp8_fp8 v[196:199], v[130:131], v[26:27], v[196:199]
	v_mfma_f32_16x16x32_fp8_fp8 v[196:199], v[132:133], v[28:29], v[196:199]
	v_mfma_f32_16x16x32_fp8_fp8 v[196:199], v[134:135], v[30:31], v[196:199]
	v_cndmask_b32_e64 v141, v141, v188, s[8:9]
	s_waitcnt vmcnt(29)
	v_mfma_f32_16x16x32_fp8_fp8 v[184:187], v[128:129], v[32:33], 0
	v_mfma_f32_16x16x32_fp8_fp8 v[184:187], v[130:131], v[34:35], v[184:187]
	v_mfma_f32_16x16x32_fp8_fp8 v[184:187], v[132:133], v[36:37], v[184:187]
	v_mfma_f32_16x16x32_fp8_fp8 v[184:187], v[134:135], v[38:39], v[184:187]
	v_cndmask_b32_e64 v142, v142, v192, s[8:9]
	s_waitcnt vmcnt(27)
	v_mfma_f32_16x16x32_fp8_fp8 v[188:191], v[128:129], v[40:41], 0
	v_mfma_f32_16x16x32_fp8_fp8 v[188:191], v[130:131], v[42:43], v[188:191]
	v_mfma_f32_16x16x32_fp8_fp8 v[188:191], v[132:133], v[44:45], v[188:191]
	v_mfma_f32_16x16x32_fp8_fp8 v[188:191], v[134:135], v[46:47], v[188:191]
	v_cndmask_b32_e64 v143, v143, v196, s[8:9]
	s_waitcnt vmcnt(25)
	v_mfma_f32_16x16x32_fp8_fp8 v[192:195], v[128:129], v[48:49], 0
	v_mfma_f32_16x16x32_fp8_fp8 v[192:195], v[130:131], v[50:51], v[192:195]
	v_mfma_f32_16x16x32_fp8_fp8 v[192:195], v[132:133], v[52:53], v[192:195]
	v_mfma_f32_16x16x32_fp8_fp8 v[192:195], v[134:135], v[54:55], v[192:195]
	v_cndmask_b32_e64 v140, v140, v184, s[10:11]
	s_waitcnt vmcnt(23)
	v_mfma_f32_16x16x32_fp8_fp8 v[196:199], v[128:129], v[56:57], 0
	v_mfma_f32_16x16x32_fp8_fp8 v[196:199], v[130:131], v[58:59], v[196:199]
	v_mfma_f32_16x16x32_fp8_fp8 v[196:199], v[132:133], v[60:61], v[196:199]
	v_mfma_f32_16x16x32_fp8_fp8 v[196:199], v[134:135], v[62:63], v[196:199]
	v_cndmask_b32_e64 v141, v141, v188, s[10:11]
	s_waitcnt vmcnt(21)
	v_mfma_f32_16x16x32_fp8_fp8 v[184:187], v[128:129], v[64:65], 0
	v_mfma_f32_16x16x32_fp8_fp8 v[184:187], v[130:131], v[66:67], v[184:187]
	v_mfma_f32_16x16x32_fp8_fp8 v[184:187], v[132:133], v[68:69], v[184:187]
	v_mfma_f32_16x16x32_fp8_fp8 v[184:187], v[134:135], v[70:71], v[184:187]
	v_cndmask_b32_e64 v142, v142, v192, s[10:11]
	s_waitcnt vmcnt(19)
	v_mfma_f32_16x16x32_fp8_fp8 v[188:191], v[128:129], v[72:73], 0
	v_mfma_f32_16x16x32_fp8_fp8 v[188:191], v[130:131], v[74:75], v[188:191]
	v_mfma_f32_16x16x32_fp8_fp8 v[188:191], v[132:133], v[76:77], v[188:191]
	v_mfma_f32_16x16x32_fp8_fp8 v[188:191], v[134:135], v[78:79], v[188:191]
	v_cndmask_b32_e64 v143, v143, v196, s[10:11]
	s_waitcnt vmcnt(17)
	v_mfma_f32_16x16x32_fp8_fp8 v[192:195], v[128:129], v[80:81], 0
	v_mfma_f32_16x16x32_fp8_fp8 v[192:195], v[130:131], v[82:83], v[192:195]
	v_mfma_f32_16x16x32_fp8_fp8 v[192:195], v[132:133], v[84:85], v[192:195]
	v_mfma_f32_16x16x32_fp8_fp8 v[192:195], v[134:135], v[86:87], v[192:195]
	v_cndmask_b32_e64 v140, v140, v184, s[16:17]
	s_waitcnt vmcnt(15)
; template <int CTRL> __device__ __forceinline__ float dpp_f(float v) { return __builtin_bit_cast(float, __builtin_amdgcn_update_dpp(0, __builtin_bit_cast(int, v), CTRL, 0xF, 0xF, true)); }
; __device__ __forceinline__ void pl32(unsigned a, unsigned b, unsigned& ra, unsigned& rb) { asm volatile("" : "+v"(b)); auto r = __builtin_amdgcn_permlane32_swap(a, b, false, false); ra = r[0]; rb = r[1]; asm volatile("" : "+v"(ra), "+v"(rb)); }
; __device__ __forceinline__ void pl16(unsigned a, unsigned b, unsigned& ra, unsigned& rb) { asm volatile("" : "+v"(b)); auto r = __builtin_amdgcn_permlane16_swap(a, b, false, false); ra = r[0]; rb = r[1]; asm volatile("" : "+v"(ra), "+v"(rb)); }
; __device__ __forceinline__ float wave_max(float v) {
;     v = fmaxf(v, dpp_f<0x128>(v)); v = fmaxf(v, dpp_f<0x124>(v)); v = fmaxf(v, dpp_f<0x4E>(v)); v = fmaxf(v, dpp_f<0xB1>(v));
;     unsigned x, y;
;     pl16(__builtin_bit_cast(unsigned, v), __builtin_bit_cast(unsigned, v), x, y); v = fmaxf(__builtin_bit_cast(float, x), __builtin_bit_cast(float, y));
;     pl32(__builtin_bit_cast(unsigned, v), __builtin_bit_cast(unsigned, v), x, y); v = fmaxf(__builtin_bit_cast(float, x), __builtin_bit_cast(float, y));
;     return v;
; }
; __device__ __forceinline__ void sparse_unit7(const bf16_t* QKV, const unsigned char* K8, const unsigned char* V8, const int (&selv)[4], bf16_t* OB, LAS unsigned char* wl, int t, int h, int lane) {
;     ...
;             for (int g = 0; g < 4; ++g) { acc[g] = (f32x4){0.f, 0.f, 0.f, 0.f};
; #pragma unroll
;                 for (int ks = 0; ks < 4; ++ks) acc[g] = __builtin_amdgcn_mfma_f32_16x16x32_fp8_fp8(qa[ks], kf[g * 4 + ks], acc[g], 0, 0, 0); }
;             float sc = (slab == 0) ? acc[0][0] : (slab == 1) ? acc[1][0] : (slab == 2) ? acc[2][0] : acc[3][0];
;             sc = valid ? sc * 0.08838834764831845f : -INFINITY;
;             const float mn = fmaxf(m, wave_max(sc));
;             const float alpha = __expf(m - mn), p = __expf(sc - mn);
;             oa = oa * alpha; ob = ob * alpha; m = mn; l = l * alpha + p;
;             pt[lane] = p;
;             asm volatile("" ::: "memory");
;             const int sn_ = (s < 3) ? (s + 1) : 3;
;             s8_issue_k(kf, K8h, wsel, 64 * sn_, n16, slab);
;             s9_pv<0>(va, pt, half, oa, ob);
	v_mfma_f32_16x16x32_fp8_fp8 v[196:199], v[128:129], v[88:89], 0
	v_mfma_f32_16x16x32_fp8_fp8 v[196:199], v[130:131], v[90:91], v[196:199]
	v_mfma_f32_16x16x32_fp8_fp8 v[196:199], v[132:133], v[92:93], v[196:199]
	v_mfma_f32_16x16x32_fp8_fp8 v[196:199], v[134:135], v[94:95], v[196:199]
	v_cndmask_b32_e64 v141, v141, v188, s[16:17]
	s_waitcnt vmcnt(13)
	v_mfma_f32_16x16x32_fp8_fp8 v[184:187], v[128:129], v[96:97], 0
	v_mfma_f32_16x16x32_fp8_fp8 v[184:187], v[130:131], v[98:99], v[184:187]
	v_mfma_f32_16x16x32_fp8_fp8 v[184:187], v[132:133], v[100:101], v[184:187]
	v_mfma_f32_16x16x32_fp8_fp8 v[184:187], v[134:135], v[102:103], v[184:187]
	v_cndmask_b32_e64 v142, v142, v192, s[16:17]
	s_waitcnt vmcnt(11)
	v_mfma_f32_16x16x32_fp8_fp8 v[188:191], v[128:129], v[104:105], 0
	v_mfma_f32_16x16x32_fp8_fp8 v[188:191], v[130:131], v[106:107], v[188:191]
	v_mfma_f32_16x16x32_fp8_fp8 v[188:191], v[132:133], v[108:109], v[188:191]
	v_mfma_f32_16x16x32_fp8_fp8 v[188:191], v[134:135], v[110:111], v[188:191]
	v_cndmask_b32_e64 v143, v143, v196, s[16:17]
	s_waitcnt vmcnt(9)
	v_mfma_f32_16x16x32_fp8_fp8 v[192:195], v[128:129], v[112:113], 0
	v_mfma_f32_16x16x32_fp8_fp8 v[192:195], v[130:131], v[114:115], v[192:195]
	v_mfma_f32_16x16x32_fp8_fp8 v[192:195], v[132:133], v[116:117], v[192:195]
	v_mfma_f32_16x16x32_fp8_fp8 v[192:195], v[134:135], v[118:119], v[192:195]
	v_cndmask_b32_e64 v140, v140, v184, s[22:23]
	s_waitcnt vmcnt(7)
	v_mfma_f32_16x16x32_fp8_fp8 v[196:199], v[128:129], v[120:121], 0
	v_mfma_f32_16x16x32_fp8_fp8 v[196:199], v[130:131], v[122:123], v[196:199]
	v_mfma_f32_16x16x32_fp8_fp8 v[196:199], v[132:133], v[124:125], v[196:199]
	v_mfma_f32_16x16x32_fp8_fp8 v[196:199], v[134:135], v[126:127], v[196:199]
	v_cndmask_b32_e64 v141, v141, v188, s[22:23]
	s_nop 7
	s_nop 7
	v_cndmask_b32_e64 v142, v142, v192, s[22:23]
	v_cndmask_b32_e64 v143, v143, v196, s[22:23]
	s_sub_i32 s99, s98, 0
	v_mul_f32_e32 v140, 0x3db504f3, v140
	v_cmp_gt_i32_e32 vcc, s99, v217
	s_nop 1
	v_cndmask_b32_e32 v140, v208, v140, vcc
	s_sub_i32 s99, s98, 1
	v_mul_f32_e32 v141, 0x3db504f3, v141
	v_cmp_gt_i32_e32 vcc, s99, v217
	s_nop 1
	v_cndmask_b32_e32 v141, v208, v141, vcc
	s_sub_i32 s99, s98, 2
	v_mul_f32_e32 v142, 0x3db504f3, v142
	v_cmp_gt_i32_e32 vcc, s99, v217
	s_nop 1
	v_cndmask_b32_e32 v142, v208, v142, vcc
	s_sub_i32 s99, s98, 3
	v_mul_f32_e32 v143, 0x3db504f3, v143
	v_cmp_gt_i32_e32 vcc, s99, v217
	s_nop 1
	v_cndmask_b32_e32 v143, v208, v143, vcc
	v_max_f32_e32 v218, v140, v141
	v_max3_f32 v218, v218, v142, v143
	s_nop 1
	v_max_f32_dpp v218, v218, v218 row_ror:8 row_mask:0xf bank_mask:0xf bound_ctrl:1
	s_nop 1
	v_max_f32_dpp v218, v218, v218 row_ror:4 row_mask:0xf bank_mask:0xf bound_ctrl:1
	s_nop 1
	v_max_f32_dpp v218, v218, v218 quad_perm:[2,3,0,1] row_mask:0xf bank_mask:0xf bound_ctrl:1
	s_nop 1
	v_max_f32_dpp v218, v218, v218 quad_perm:[1,0,3,2] row_mask:0xf bank_mask:0xf bound_ctrl:1
	v_mov_b32_e32 v219, v218
	s_nop 1
	v_permlane16_swap_b32_e32 v218, v219
	s_nop 1
	v_max_f32_e32 v218, v218, v219
	v_mov_b32_e32 v219, v218
	s_nop 1
	v_permlane32_swap_b32_e32 v218, v219
	s_nop 1
	v_max_f32_e32 v218, v218, v219
	v_sub_f32_e32 v140, v140, v218
	v_sub_f32_e32 v141, v141, v218
	v_sub_f32_e32 v142, v142, v218
	v_sub_f32_e32 v143, v143, v218
	v_mul_f32_e32 v140, 0x3fb8aa3b, v140
	v_mul_f32_e32 v141, 0x3fb8aa3b, v141
	v_mul_f32_e32 v142, 0x3fb8aa3b, v142
	v_mul_f32_e32 v143, 0x3fb8aa3b, v143
	v_exp_f32_e32 v140, v140
	v_exp_f32_e32 v141, v141
	v_exp_f32_e32 v142, v142
	v_exp_f32_e32 v143, v143
	s_nop 1
	ds_write_b128 v213, v[140:143]
	ds_write_b128 v213, v[136:139] offset:1152
	v_add_f32_e32 v246, v140, v141
	v_add_f32_e32 v247, v142, v143
	v_add_f32_e32 v246, v246, v247
	ds_read_b128 v[64:67], v214 offset:1152
	ds_read_b128 v[68:71], v214 offset:1168
	ds_read_b128 v[72:75], v214 offset:1184
	ds_read_b128 v[76:79], v214 offset:1200
	ds_read_b128 v[80:83], v214 offset:1216
	ds_read_b128 v[84:87], v214 offset:1232
	ds_read_b128 v[88:91], v214 offset:1248
	ds_read_b128 v[92:95], v214 offset:1264
	ds_read_b128 v[96:99], v214 offset:0
	ds_read_b128 v[100:103], v214 offset:16
	ds_read_b128 v[104:107], v214 offset:32
	ds_read_b128 v[108:111], v214 offset:48
	ds_read_b128 v[112:115], v214 offset:64
	ds_read_b128 v[116:119], v214 offset:80
	ds_read_b128 v[120:123], v214 offset:96
	ds_read_b128 v[124:127], v214 offset:112
	v_mov_b32_e32 v144, 0
	v_mov_b32_e32 v145, 0
	v_mov_b32_e32 v146, 0
	v_mov_b32_e32 v147, 0
	v_mov_b32_e32 v148, 0
	v_mov_b32_e32 v149, 0
	v_mov_b32_e32 v150, 0
	v_mov_b32_e32 v151, 0
	v_mov_b32_e32 v152, 0
	v_mov_b32_e32 v153, 0
	v_mov_b32_e32 v154, 0
	v_mov_b32_e32 v155, 0
	v_mov_b32_e32 v156, 0
	v_mov_b32_e32 v157, 0
	v_mov_b32_e32 v158, 0
	v_mov_b32_e32 v159, 0
	s_waitcnt lgkmcnt(8)
; #define LAS __attribute__((address_space(3)))
; template <int CTRL> __device__ __forceinline__ float dpp_f(float v) { return __builtin_bit_cast(float, __builtin_amdgcn_update_dpp(0, __builtin_bit_cast(int, v), CTRL, 0xF, 0xF, true)); }
; __device__ __forceinline__ float swap32_sum(float a, float b) { unsigned x, y; pl32(__builtin_bit_cast(unsigned, a), __builtin_bit_cast(unsigned, b), x, y); return __builtin_bit_cast(float, x) + __builtin_bit_cast(float, y); }
; __device__ __forceinline__ float swap16_sum(float a, float b) { unsigned x, y; pl16(__builtin_bit_cast(unsigned, a), __builtin_bit_cast(unsigned, b), x, y); return __builtin_bit_cast(float, x) + __builtin_bit_cast(float, y); }
; __device__ __forceinline__ float wave_sum(float v) {
;     v += dpp_f<0x128>(v); v += dpp_f<0x124>(v); v += dpp_f<0x4E>(v); v += dpp_f<0xB1>(v);
;     v = swap16_sum(v, v); return swap32_sum(v, v);
; }
; template <int Q> __device__ __forceinline__ void s9_issue_v(unsigned (&vv)[8], const unsigned char* V8h, LAS const unsigned* otw, int half, int l4) {
; #pragma unroll
;     for (int u2 = 0; u2 < 8; ++u2) vv[u2] = *(const unsigned*)(V8h + (otw[2 * (Q * 8 + u2) + half] | (unsigned)l4));
; }
; template <int Q> __device__ __forceinline__ void s9_pv(const unsigned (&vv)[8], LAS const float* ptw, int half, f32x2_t& oa, f32x2_t& ob) {
; #pragma unroll
;     for (int u2 = 0; u2 < 8; ++u2) { const float p = ptw[2 * (Q * 8 + u2) + half];
;         oa = __builtin_amdgcn_cvt_pk_f32_fp8((int)vv[u2], false) * p + oa; ob = __builtin_amdgcn_cvt_pk_f32_fp8((int)vv[u2], true) * p + ob; }
; }
	v_or_b32_e32 v218, v64, v203
	global_load_dwordx4 v[0:3], v218, s[44:45]
	v_or_b32_e32 v218, v65, v203
	global_load_dwordx4 v[4:7], v218, s[44:45]
	v_or_b32_e32 v218, v66, v203
	global_load_dwordx4 v[8:11], v218, s[44:45]
	v_or_b32_e32 v218, v67, v203
	global_load_dwordx4 v[12:15], v218, s[44:45]
	v_or_b32_e32 v218, v68, v203
	global_load_dwordx4 v[16:19], v218, s[44:45]
	v_or_b32_e32 v218, v69, v203
	global_load_dwordx4 v[20:23], v218, s[44:45]
	v_or_b32_e32 v218, v70, v203
	global_load_dwordx4 v[24:27], v218, s[44:45]
	v_or_b32_e32 v218, v71, v203
	global_load_dwordx4 v[28:31], v218, s[44:45]
	v_or_b32_e32 v218, v72, v203
	global_load_dwordx4 v[32:35], v218, s[44:45]
	v_or_b32_e32 v218, v73, v203
	global_load_dwordx4 v[36:39], v218, s[44:45]
	v_or_b32_e32 v218, v74, v203
	global_load_dwordx4 v[40:43], v218, s[44:45]
	v_or_b32_e32 v218, v75, v203
	global_load_dwordx4 v[44:47], v218, s[44:45]
	v_or_b32_e32 v218, v76, v203
	global_load_dwordx4 v[48:51], v218, s[44:45]
	v_or_b32_e32 v218, v77, v203
	global_load_dwordx4 v[52:55], v218, s[44:45]
	v_or_b32_e32 v218, v78, v203
	global_load_dwordx4 v[56:59], v218, s[44:45]
	v_or_b32_e32 v218, v79, v203
	global_load_dwordx4 v[60:63], v218, s[44:45]
	s_nop 1
	v_add_f32_dpp v246, v246, v246 row_ror:8 row_mask:0xf bank_mask:0xf bound_ctrl:1
	s_nop 1
	v_add_f32_dpp v246, v246, v246 row_ror:4 row_mask:0xf bank_mask:0xf bound_ctrl:1
	s_nop 1
	v_add_f32_dpp v246, v246, v246 quad_perm:[2,3,0,1] row_mask:0xf bank_mask:0xf bound_ctrl:1
	s_nop 1
	v_add_f32_dpp v246, v246, v246 quad_perm:[1,0,3,2] row_mask:0xf bank_mask:0xf bound_ctrl:1
	v_mov_b32_e32 v247, v246
	s_nop 1
	v_permlane16_swap_b32_e32 v246, v247
	s_nop 1
	v_add_f32_e32 v246, v246, v247
	v_mov_b32_e32 v247, v246
	s_nop 1
	v_permlane32_swap_b32_e32 v246, v247
	s_nop 1
	v_add_f32_e32 v246, v246, v247
	s_waitcnt lgkmcnt(0)
	s_waitcnt vmcnt(15)
	v_cvt_pk_f32_fp8_e32 v[184:185], v0
	v_cvt_pk_f32_fp8_sdwa v[186:187], v0 src0_sel:WORD_1
	v_cvt_pk_f32_fp8_e32 v[188:189], v1
	v_cvt_pk_f32_fp8_sdwa v[190:191], v1 src0_sel:WORD_1
	v_cvt_pk_f32_fp8_e32 v[192:193], v2
	v_cvt_pk_f32_fp8_sdwa v[194:195], v2 src0_sel:WORD_1
	v_cvt_pk_f32_fp8_e32 v[196:197], v3
	v_cvt_pk_f32_fp8_sdwa v[198:199], v3 src0_sel:WORD_1
	v_or_b32_e32 v218, v80, v203
	global_load_dwordx4 v[0:3], v218, s[44:45]
	v_pk_fma_f32 v[144:145], v[184:185], v[96:97], v[144:145] op_sel_hi:[1,0,1]
	v_pk_fma_f32 v[146:147], v[186:187], v[96:97], v[146:147] op_sel_hi:[1,0,1]
	v_pk_fma_f32 v[148:149], v[188:189], v[96:97], v[148:149] op_sel_hi:[1,0,1]
	v_pk_fma_f32 v[150:151], v[190:191], v[96:97], v[150:151] op_sel_hi:[1,0,1]
	v_pk_fma_f32 v[152:153], v[192:193], v[96:97], v[152:153] op_sel_hi:[1,0,1]
	v_pk_fma_f32 v[154:155], v[194:195], v[96:97], v[154:155] op_sel_hi:[1,0,1]
	v_pk_fma_f32 v[156:157], v[196:197], v[96:97], v[156:157] op_sel_hi:[1,0,1]
	v_pk_fma_f32 v[158:159], v[198:199], v[96:97], v[158:159] op_sel_hi:[1,0,1]
	s_waitcnt vmcnt(15)
	v_cvt_pk_f32_fp8_e32 v[184:185], v4
	v_cvt_pk_f32_fp8_sdwa v[186:187], v4 src0_sel:WORD_1
	v_cvt_pk_f32_fp8_e32 v[188:189], v5
	v_cvt_pk_f32_fp8_sdwa v[190:191], v5 src0_sel:WORD_1
	v_cvt_pk_f32_fp8_e32 v[192:193], v6
	v_cvt_pk_f32_fp8_sdwa v[194:195], v6 src0_sel:WORD_1
	v_cvt_pk_f32_fp8_e32 v[196:197], v7
	v_cvt_pk_f32_fp8_sdwa v[198:199], v7 src0_sel:WORD_1
	v_or_b32_e32 v218, v81, v203
	global_load_dwordx4 v[4:7], v218, s[44:45]
	v_pk_fma_f32 v[144:145], v[184:185], v[96:97], v[144:145] op_sel:[0,1,0] op_sel_hi:[1,1,1]
	v_pk_fma_f32 v[146:147], v[186:187], v[96:97], v[146:147] op_sel:[0,1,0] op_sel_hi:[1,1,1]
	v_pk_fma_f32 v[148:149], v[188:189], v[96:97], v[148:149] op_sel:[0,1,0] op_sel_hi:[1,1,1]
	v_pk_fma_f32 v[150:151], v[190:191], v[96:97], v[150:151] op_sel:[0,1,0] op_sel_hi:[1,1,1]
	v_pk_fma_f32 v[152:153], v[192:193], v[96:97], v[152:153] op_sel:[0,1,0] op_sel_hi:[1,1,1]
	v_pk_fma_f32 v[154:155], v[194:195], v[96:97], v[154:155] op_sel:[0,1,0] op_sel_hi:[1,1,1]
	v_pk_fma_f32 v[156:157], v[196:197], v[96:97], v[156:157] op_sel:[0,1,0] op_sel_hi:[1,1,1]
	v_pk_fma_f32 v[158:159], v[198:199], v[96:97], v[158:159] op_sel:[0,1,0] op_sel_hi:[1,1,1]
	s_waitcnt vmcnt(15)
	v_cvt_pk_f32_fp8_e32 v[184:185], v8
	v_cvt_pk_f32_fp8_sdwa v[186:187], v8 src0_sel:WORD_1
	v_cvt_pk_f32_fp8_e32 v[188:189], v9
	v_cvt_pk_f32_fp8_sdwa v[190:191], v9 src0_sel:WORD_1
	v_cvt_pk_f32_fp8_e32 v[192:193], v10
	v_cvt_pk_f32_fp8_sdwa v[194:195], v10 src0_sel:WORD_1
	v_cvt_pk_f32_fp8_e32 v[196:197], v11
	v_cvt_pk_f32_fp8_sdwa v[198:199], v11 src0_sel:WORD_1
	v_or_b32_e32 v218, v82, v203
	global_load_dwordx4 v[8:11], v218, s[44:45]
	v_pk_fma_f32 v[144:145], v[184:185], v[98:99], v[144:145] op_sel_hi:[1,0,1]
	v_pk_fma_f32 v[146:147], v[186:187], v[98:99], v[146:147] op_sel_hi:[1,0,1]
	v_pk_fma_f32 v[148:149], v[188:189], v[98:99], v[148:149] op_sel_hi:[1,0,1]
	v_pk_fma_f32 v[150:151], v[190:191], v[98:99], v[150:151] op_sel_hi:[1,0,1]
	v_pk_fma_f32 v[152:153], v[192:193], v[98:99], v[152:153] op_sel_hi:[1,0,1]
	v_pk_fma_f32 v[154:155], v[194:195], v[98:99], v[154:155] op_sel_hi:[1,0,1]
	v_pk_fma_f32 v[156:157], v[196:197], v[98:99], v[156:157] op_sel_hi:[1,0,1]
	v_pk_fma_f32 v[158:159], v[198:199], v[98:99], v[158:159] op_sel_hi:[1,0,1]
	s_waitcnt vmcnt(15)
; #define LAS __attribute__((address_space(3)))
; template <int Q> __device__ __forceinline__ void s9_pv(const unsigned (&vv)[8], LAS const float* ptw, int half, f32x2_t& oa, f32x2_t& ob) {
; #pragma unroll
;     for (int u2 = 0; u2 < 8; ++u2) { const float p = ptw[2 * (Q * 8 + u2) + half];
;         oa = __builtin_amdgcn_cvt_pk_f32_fp8((int)vv[u2], false) * p + oa; ob = __builtin_amdgcn_cvt_pk_f32_fp8((int)vv[u2], true) * p + ob; }
; }
	v_cvt_pk_f32_fp8_e32 v[184:185], v12
	v_cvt_pk_f32_fp8_sdwa v[186:187], v12 src0_sel:WORD_1
	v_cvt_pk_f32_fp8_e32 v[188:189], v13
	v_cvt_pk_f32_fp8_sdwa v[190:191], v13 src0_sel:WORD_1
	v_cvt_pk_f32_fp8_e32 v[192:193], v14
	v_cvt_pk_f32_fp8_sdwa v[194:195], v14 src0_sel:WORD_1
	v_cvt_pk_f32_fp8_e32 v[196:197], v15
	v_cvt_pk_f32_fp8_sdwa v[198:199], v15 src0_sel:WORD_1
	v_or_b32_e32 v218, v83, v203
	global_load_dwordx4 v[12:15], v218, s[44:45]
	v_pk_fma_f32 v[144:145], v[184:185], v[98:99], v[144:145] op_sel:[0,1,0] op_sel_hi:[1,1,1]
	v_pk_fma_f32 v[146:147], v[186:187], v[98:99], v[146:147] op_sel:[0,1,0] op_sel_hi:[1,1,1]
	v_pk_fma_f32 v[148:149], v[188:189], v[98:99], v[148:149] op_sel:[0,1,0] op_sel_hi:[1,1,1]
	v_pk_fma_f32 v[150:151], v[190:191], v[98:99], v[150:151] op_sel:[0,1,0] op_sel_hi:[1,1,1]
	v_pk_fma_f32 v[152:153], v[192:193], v[98:99], v[152:153] op_sel:[0,1,0] op_sel_hi:[1,1,1]
	v_pk_fma_f32 v[154:155], v[194:195], v[98:99], v[154:155] op_sel:[0,1,0] op_sel_hi:[1,1,1]
	v_pk_fma_f32 v[156:157], v[196:197], v[98:99], v[156:157] op_sel:[0,1,0] op_sel_hi:[1,1,1]
	v_pk_fma_f32 v[158:159], v[198:199], v[98:99], v[158:159] op_sel:[0,1,0] op_sel_hi:[1,1,1]
	s_waitcnt vmcnt(15)
	v_cvt_pk_f32_fp8_e32 v[184:185], v16
	v_cvt_pk_f32_fp8_sdwa v[186:187], v16 src0_sel:WORD_1
	v_cvt_pk_f32_fp8_e32 v[188:189], v17
	v_cvt_pk_f32_fp8_sdwa v[190:191], v17 src0_sel:WORD_1
	v_cvt_pk_f32_fp8_e32 v[192:193], v18
	v_cvt_pk_f32_fp8_sdwa v[194:195], v18 src0_sel:WORD_1
	v_cvt_pk_f32_fp8_e32 v[196:197], v19
	v_cvt_pk_f32_fp8_sdwa v[198:199], v19 src0_sel:WORD_1
	v_or_b32_e32 v218, v84, v203
	global_load_dwordx4 v[16:19], v218, s[44:45]
	v_pk_fma_f32 v[144:145], v[184:185], v[100:101], v[144:145] op_sel_hi:[1,0,1]
	v_pk_fma_f32 v[146:147], v[186:187], v[100:101], v[146:147] op_sel_hi:[1,0,1]
	v_pk_fma_f32 v[148:149], v[188:189], v[100:101], v[148:149] op_sel_hi:[1,0,1]
	v_pk_fma_f32 v[150:151], v[190:191], v[100:101], v[150:151] op_sel_hi:[1,0,1]
	v_pk_fma_f32 v[152:153], v[192:193], v[100:101], v[152:153] op_sel_hi:[1,0,1]
	v_pk_fma_f32 v[154:155], v[194:195], v[100:101], v[154:155] op_sel_hi:[1,0,1]
	v_pk_fma_f32 v[156:157], v[196:197], v[100:101], v[156:157] op_sel_hi:[1,0,1]
	v_pk_fma_f32 v[158:159], v[198:199], v[100:101], v[158:159] op_sel_hi:[1,0,1]
	s_waitcnt vmcnt(15)
	v_cvt_pk_f32_fp8_e32 v[184:185], v20
	v_cvt_pk_f32_fp8_sdwa v[186:187], v20 src0_sel:WORD_1
	v_cvt_pk_f32_fp8_e32 v[188:189], v21
	v_cvt_pk_f32_fp8_sdwa v[190:191], v21 src0_sel:WORD_1
	v_cvt_pk_f32_fp8_e32 v[192:193], v22
	v_cvt_pk_f32_fp8_sdwa v[194:195], v22 src0_sel:WORD_1
	v_cvt_pk_f32_fp8_e32 v[196:197], v23
	v_cvt_pk_f32_fp8_sdwa v[198:199], v23 src0_sel:WORD_1
	v_or_b32_e32 v218, v85, v203
	global_load_dwordx4 v[20:23], v218, s[44:45]
	v_pk_fma_f32 v[144:145], v[184:185], v[100:101], v[144:145] op_sel:[0,1,0] op_sel_hi:[1,1,1]
	v_pk_fma_f32 v[146:147], v[186:187], v[100:101], v[146:147] op_sel:[0,1,0] op_sel_hi:[1,1,1]
	v_pk_fma_f32 v[148:149], v[188:189], v[100:101], v[148:149] op_sel:[0,1,0] op_sel_hi:[1,1,1]
	v_pk_fma_f32 v[150:151], v[190:191], v[100:101], v[150:151] op_sel:[0,1,0] op_sel_hi:[1,1,1]
	v_pk_fma_f32 v[152:153], v[192:193], v[100:101], v[152:153] op_sel:[0,1,0] op_sel_hi:[1,1,1]
	v_pk_fma_f32 v[154:155], v[194:195], v[100:101], v[154:155] op_sel:[0,1,0] op_sel_hi:[1,1,1]
	v_pk_fma_f32 v[156:157], v[196:197], v[100:101], v[156:157] op_sel:[0,1,0] op_sel_hi:[1,1,1]
	v_pk_fma_f32 v[158:159], v[198:199], v[100:101], v[158:159] op_sel:[0,1,0] op_sel_hi:[1,1,1]
	s_waitcnt vmcnt(15)
	v_cvt_pk_f32_fp8_e32 v[184:185], v24
	v_cvt_pk_f32_fp8_sdwa v[186:187], v24 src0_sel:WORD_1
	v_cvt_pk_f32_fp8_e32 v[188:189], v25
	v_cvt_pk_f32_fp8_sdwa v[190:191], v25 src0_sel:WORD_1
	v_cvt_pk_f32_fp8_e32 v[192:193], v26
	v_cvt_pk_f32_fp8_sdwa v[194:195], v26 src0_sel:WORD_1
	v_cvt_pk_f32_fp8_e32 v[196:197], v27
	v_cvt_pk_f32_fp8_sdwa v[198:199], v27 src0_sel:WORD_1
	v_or_b32_e32 v218, v86, v203
	global_load_dwordx4 v[24:27], v218, s[44:45]
	v_pk_fma_f32 v[144:145], v[184:185], v[102:103], v[144:145] op_sel_hi:[1,0,1]
	v_pk_fma_f32 v[146:147], v[186:187], v[102:103], v[146:147] op_sel_hi:[1,0,1]
	v_pk_fma_f32 v[148:149], v[188:189], v[102:103], v[148:149] op_sel_hi:[1,0,1]
	v_pk_fma_f32 v[150:151], v[190:191], v[102:103], v[150:151] op_sel_hi:[1,0,1]
	v_pk_fma_f32 v[152:153], v[192:193], v[102:103], v[152:153] op_sel_hi:[1,0,1]
	v_pk_fma_f32 v[154:155], v[194:195], v[102:103], v[154:155] op_sel_hi:[1,0,1]
	v_pk_fma_f32 v[156:157], v[196:197], v[102:103], v[156:157] op_sel_hi:[1,0,1]
	v_pk_fma_f32 v[158:159], v[198:199], v[102:103], v[158:159] op_sel_hi:[1,0,1]
	s_waitcnt vmcnt(15)
	v_cvt_pk_f32_fp8_e32 v[184:185], v28
	v_cvt_pk_f32_fp8_sdwa v[186:187], v28 src0_sel:WORD_1
	v_cvt_pk_f32_fp8_e32 v[188:189], v29
	v_cvt_pk_f32_fp8_sdwa v[190:191], v29 src0_sel:WORD_1
	v_cvt_pk_f32_fp8_e32 v[192:193], v30
	v_cvt_pk_f32_fp8_sdwa v[194:195], v30 src0_sel:WORD_1
	v_cvt_pk_f32_fp8_e32 v[196:197], v31
	v_cvt_pk_f32_fp8_sdwa v[198:199], v31 src0_sel:WORD_1
	v_or_b32_e32 v218, v87, v203
	global_load_dwordx4 v[28:31], v218, s[44:45]
	v_pk_fma_f32 v[144:145], v[184:185], v[102:103], v[144:145] op_sel:[0,1,0] op_sel_hi:[1,1,1]
	v_pk_fma_f32 v[146:147], v[186:187], v[102:103], v[146:147] op_sel:[0,1,0] op_sel_hi:[1,1,1]
	v_pk_fma_f32 v[148:149], v[188:189], v[102:103], v[148:149] op_sel:[0,1,0] op_sel_hi:[1,1,1]
	v_pk_fma_f32 v[150:151], v[190:191], v[102:103], v[150:151] op_sel:[0,1,0] op_sel_hi:[1,1,1]
	v_pk_fma_f32 v[152:153], v[192:193], v[102:103], v[152:153] op_sel:[0,1,0] op_sel_hi:[1,1,1]
	v_pk_fma_f32 v[154:155], v[194:195], v[102:103], v[154:155] op_sel:[0,1,0] op_sel_hi:[1,1,1]
	v_pk_fma_f32 v[156:157], v[196:197], v[102:103], v[156:157] op_sel:[0,1,0] op_sel_hi:[1,1,1]
	v_pk_fma_f32 v[158:159], v[198:199], v[102:103], v[158:159] op_sel:[0,1,0] op_sel_hi:[1,1,1]
	s_waitcnt vmcnt(15)
; #define LAS __attribute__((address_space(3)))
; template <int Q> __device__ __forceinline__ void s9_pv(const unsigned (&vv)[8], LAS const float* ptw, int half, f32x2_t& oa, f32x2_t& ob) {
; #pragma unroll
;     for (int u2 = 0; u2 < 8; ++u2) { const float p = ptw[2 * (Q * 8 + u2) + half];
;         oa = __builtin_amdgcn_cvt_pk_f32_fp8((int)vv[u2], false) * p + oa; ob = __builtin_amdgcn_cvt_pk_f32_fp8((int)vv[u2], true) * p + ob; }
; }
	v_cvt_pk_f32_fp8_e32 v[184:185], v32
	v_cvt_pk_f32_fp8_sdwa v[186:187], v32 src0_sel:WORD_1
	v_cvt_pk_f32_fp8_e32 v[188:189], v33
	v_cvt_pk_f32_fp8_sdwa v[190:191], v33 src0_sel:WORD_1
	v_cvt_pk_f32_fp8_e32 v[192:193], v34
	v_cvt_pk_f32_fp8_sdwa v[194:195], v34 src0_sel:WORD_1
	v_cvt_pk_f32_fp8_e32 v[196:197], v35
	v_cvt_pk_f32_fp8_sdwa v[198:199], v35 src0_sel:WORD_1
	v_or_b32_e32 v218, v88, v203
	global_load_dwordx4 v[32:35], v218, s[44:45]
	v_pk_fma_f32 v[144:145], v[184:185], v[104:105], v[144:145] op_sel_hi:[1,0,1]
	v_pk_fma_f32 v[146:147], v[186:187], v[104:105], v[146:147] op_sel_hi:[1,0,1]
	v_pk_fma_f32 v[148:149], v[188:189], v[104:105], v[148:149] op_sel_hi:[1,0,1]
	v_pk_fma_f32 v[150:151], v[190:191], v[104:105], v[150:151] op_sel_hi:[1,0,1]
	v_pk_fma_f32 v[152:153], v[192:193], v[104:105], v[152:153] op_sel_hi:[1,0,1]
	v_pk_fma_f32 v[154:155], v[194:195], v[104:105], v[154:155] op_sel_hi:[1,0,1]
	v_pk_fma_f32 v[156:157], v[196:197], v[104:105], v[156:157] op_sel_hi:[1,0,1]
	v_pk_fma_f32 v[158:159], v[198:199], v[104:105], v[158:159] op_sel_hi:[1,0,1]
	s_waitcnt vmcnt(15)
	v_cvt_pk_f32_fp8_e32 v[184:185], v36
	v_cvt_pk_f32_fp8_sdwa v[186:187], v36 src0_sel:WORD_1
	v_cvt_pk_f32_fp8_e32 v[188:189], v37
	v_cvt_pk_f32_fp8_sdwa v[190:191], v37 src0_sel:WORD_1
	v_cvt_pk_f32_fp8_e32 v[192:193], v38
	v_cvt_pk_f32_fp8_sdwa v[194:195], v38 src0_sel:WORD_1
	v_cvt_pk_f32_fp8_e32 v[196:197], v39
	v_cvt_pk_f32_fp8_sdwa v[198:199], v39 src0_sel:WORD_1
	v_or_b32_e32 v218, v89, v203
	global_load_dwordx4 v[36:39], v218, s[44:45]
	v_pk_fma_f32 v[144:145], v[184:185], v[104:105], v[144:145] op_sel:[0,1,0] op_sel_hi:[1,1,1]
	v_pk_fma_f32 v[146:147], v[186:187], v[104:105], v[146:147] op_sel:[0,1,0] op_sel_hi:[1,1,1]
	v_pk_fma_f32 v[148:149], v[188:189], v[104:105], v[148:149] op_sel:[0,1,0] op_sel_hi:[1,1,1]
	v_pk_fma_f32 v[150:151], v[190:191], v[104:105], v[150:151] op_sel:[0,1,0] op_sel_hi:[1,1,1]
	v_pk_fma_f32 v[152:153], v[192:193], v[104:105], v[152:153] op_sel:[0,1,0] op_sel_hi:[1,1,1]
	v_pk_fma_f32 v[154:155], v[194:195], v[104:105], v[154:155] op_sel:[0,1,0] op_sel_hi:[1,1,1]
	v_pk_fma_f32 v[156:157], v[196:197], v[104:105], v[156:157] op_sel:[0,1,0] op_sel_hi:[1,1,1]
	v_pk_fma_f32 v[158:159], v[198:199], v[104:105], v[158:159] op_sel:[0,1,0] op_sel_hi:[1,1,1]
	s_waitcnt vmcnt(15)
	v_cvt_pk_f32_fp8_e32 v[184:185], v40
	v_cvt_pk_f32_fp8_sdwa v[186:187], v40 src0_sel:WORD_1
	v_cvt_pk_f32_fp8_e32 v[188:189], v41
	v_cvt_pk_f32_fp8_sdwa v[190:191], v41 src0_sel:WORD_1
	v_cvt_pk_f32_fp8_e32 v[192:193], v42
	v_cvt_pk_f32_fp8_sdwa v[194:195], v42 src0_sel:WORD_1
	v_cvt_pk_f32_fp8_e32 v[196:197], v43
	v_cvt_pk_f32_fp8_sdwa v[198:199], v43 src0_sel:WORD_1
	v_or_b32_e32 v218, v90, v203
	global_load_dwordx4 v[40:43], v218, s[44:45]
	v_pk_fma_f32 v[144:145], v[184:185], v[106:107], v[144:145] op_sel_hi:[1,0,1]
	v_pk_fma_f32 v[146:147], v[186:187], v[106:107], v[146:147] op_sel_hi:[1,0,1]
	v_pk_fma_f32 v[148:149], v[188:189], v[106:107], v[148:149] op_sel_hi:[1,0,1]
	v_pk_fma_f32 v[150:151], v[190:191], v[106:107], v[150:151] op_sel_hi:[1,0,1]
	v_pk_fma_f32 v[152:153], v[192:193], v[106:107], v[152:153] op_sel_hi:[1,0,1]
	v_pk_fma_f32 v[154:155], v[194:195], v[106:107], v[154:155] op_sel_hi:[1,0,1]
	v_pk_fma_f32 v[156:157], v[196:197], v[106:107], v[156:157] op_sel_hi:[1,0,1]
	v_pk_fma_f32 v[158:159], v[198:199], v[106:107], v[158:159] op_sel_hi:[1,0,1]
	s_waitcnt vmcnt(15)
	v_cvt_pk_f32_fp8_e32 v[184:185], v44
	v_cvt_pk_f32_fp8_sdwa v[186:187], v44 src0_sel:WORD_1
	v_cvt_pk_f32_fp8_e32 v[188:189], v45
	v_cvt_pk_f32_fp8_sdwa v[190:191], v45 src0_sel:WORD_1
	v_cvt_pk_f32_fp8_e32 v[192:193], v46
	v_cvt_pk_f32_fp8_sdwa v[194:195], v46 src0_sel:WORD_1
	v_cvt_pk_f32_fp8_e32 v[196:197], v47
	v_cvt_pk_f32_fp8_sdwa v[198:199], v47 src0_sel:WORD_1
	v_or_b32_e32 v218, v91, v203
	global_load_dwordx4 v[44:47], v218, s[44:45]
	v_pk_fma_f32 v[144:145], v[184:185], v[106:107], v[144:145] op_sel:[0,1,0] op_sel_hi:[1,1,1]
	v_pk_fma_f32 v[146:147], v[186:187], v[106:107], v[146:147] op_sel:[0,1,0] op_sel_hi:[1,1,1]
	v_pk_fma_f32 v[148:149], v[188:189], v[106:107], v[148:149] op_sel:[0,1,0] op_sel_hi:[1,1,1]
	v_pk_fma_f32 v[150:151], v[190:191], v[106:107], v[150:151] op_sel:[0,1,0] op_sel_hi:[1,1,1]
	v_pk_fma_f32 v[152:153], v[192:193], v[106:107], v[152:153] op_sel:[0,1,0] op_sel_hi:[1,1,1]
	v_pk_fma_f32 v[154:155], v[194:195], v[106:107], v[154:155] op_sel:[0,1,0] op_sel_hi:[1,1,1]
	v_pk_fma_f32 v[156:157], v[196:197], v[106:107], v[156:157] op_sel:[0,1,0] op_sel_hi:[1,1,1]
	v_pk_fma_f32 v[158:159], v[198:199], v[106:107], v[158:159] op_sel:[0,1,0] op_sel_hi:[1,1,1]
	s_waitcnt vmcnt(15)
	v_cvt_pk_f32_fp8_e32 v[184:185], v48
	v_cvt_pk_f32_fp8_sdwa v[186:187], v48 src0_sel:WORD_1
	v_cvt_pk_f32_fp8_e32 v[188:189], v49
	v_cvt_pk_f32_fp8_sdwa v[190:191], v49 src0_sel:WORD_1
	v_cvt_pk_f32_fp8_e32 v[192:193], v50
	v_cvt_pk_f32_fp8_sdwa v[194:195], v50 src0_sel:WORD_1
	v_cvt_pk_f32_fp8_e32 v[196:197], v51
	v_cvt_pk_f32_fp8_sdwa v[198:199], v51 src0_sel:WORD_1
	v_or_b32_e32 v218, v92, v203
	global_load_dwordx4 v[48:51], v218, s[44:45]
	v_pk_fma_f32 v[144:145], v[184:185], v[108:109], v[144:145] op_sel_hi:[1,0,1]
	v_pk_fma_f32 v[146:147], v[186:187], v[108:109], v[146:147] op_sel_hi:[1,0,1]
	v_pk_fma_f32 v[148:149], v[188:189], v[108:109], v[148:149] op_sel_hi:[1,0,1]
	v_pk_fma_f32 v[150:151], v[190:191], v[108:109], v[150:151] op_sel_hi:[1,0,1]
	v_pk_fma_f32 v[152:153], v[192:193], v[108:109], v[152:153] op_sel_hi:[1,0,1]
	v_pk_fma_f32 v[154:155], v[194:195], v[108:109], v[154:155] op_sel_hi:[1,0,1]
	v_pk_fma_f32 v[156:157], v[196:197], v[108:109], v[156:157] op_sel_hi:[1,0,1]
	v_pk_fma_f32 v[158:159], v[198:199], v[108:109], v[158:159] op_sel_hi:[1,0,1]
	s_waitcnt vmcnt(15)
; #define LAS __attribute__((address_space(3)))
; template <int Q> __device__ __forceinline__ void s9_pv(const unsigned (&vv)[8], LAS const float* ptw, int half, f32x2_t& oa, f32x2_t& ob) {
; #pragma unroll
;     for (int u2 = 0; u2 < 8; ++u2) { const float p = ptw[2 * (Q * 8 + u2) + half];
;         oa = __builtin_amdgcn_cvt_pk_f32_fp8((int)vv[u2], false) * p + oa; ob = __builtin_amdgcn_cvt_pk_f32_fp8((int)vv[u2], true) * p + ob; }
; }
	v_cvt_pk_f32_fp8_e32 v[184:185], v52
	v_cvt_pk_f32_fp8_sdwa v[186:187], v52 src0_sel:WORD_1
	v_cvt_pk_f32_fp8_e32 v[188:189], v53
	v_cvt_pk_f32_fp8_sdwa v[190:191], v53 src0_sel:WORD_1
	v_cvt_pk_f32_fp8_e32 v[192:193], v54
	v_cvt_pk_f32_fp8_sdwa v[194:195], v54 src0_sel:WORD_1
	v_cvt_pk_f32_fp8_e32 v[196:197], v55
	v_cvt_pk_f32_fp8_sdwa v[198:199], v55 src0_sel:WORD_1
	v_or_b32_e32 v218, v93, v203
	global_load_dwordx4 v[52:55], v218, s[44:45]
	v_pk_fma_f32 v[144:145], v[184:185], v[108:109], v[144:145] op_sel:[0,1,0] op_sel_hi:[1,1,1]
	v_pk_fma_f32 v[146:147], v[186:187], v[108:109], v[146:147] op_sel:[0,1,0] op_sel_hi:[1,1,1]
	v_pk_fma_f32 v[148:149], v[188:189], v[108:109], v[148:149] op_sel:[0,1,0] op_sel_hi:[1,1,1]
	v_pk_fma_f32 v[150:151], v[190:191], v[108:109], v[150:151] op_sel:[0,1,0] op_sel_hi:[1,1,1]
	v_pk_fma_f32 v[152:153], v[192:193], v[108:109], v[152:153] op_sel:[0,1,0] op_sel_hi:[1,1,1]
	v_pk_fma_f32 v[154:155], v[194:195], v[108:109], v[154:155] op_sel:[0,1,0] op_sel_hi:[1,1,1]
	v_pk_fma_f32 v[156:157], v[196:197], v[108:109], v[156:157] op_sel:[0,1,0] op_sel_hi:[1,1,1]
	v_pk_fma_f32 v[158:159], v[198:199], v[108:109], v[158:159] op_sel:[0,1,0] op_sel_hi:[1,1,1]
	s_waitcnt vmcnt(15)
	v_cvt_pk_f32_fp8_e32 v[184:185], v56
	v_cvt_pk_f32_fp8_sdwa v[186:187], v56 src0_sel:WORD_1
	v_cvt_pk_f32_fp8_e32 v[188:189], v57
	v_cvt_pk_f32_fp8_sdwa v[190:191], v57 src0_sel:WORD_1
	v_cvt_pk_f32_fp8_e32 v[192:193], v58
	v_cvt_pk_f32_fp8_sdwa v[194:195], v58 src0_sel:WORD_1
	v_cvt_pk_f32_fp8_e32 v[196:197], v59
	v_cvt_pk_f32_fp8_sdwa v[198:199], v59 src0_sel:WORD_1
	v_or_b32_e32 v218, v94, v203
	global_load_dwordx4 v[56:59], v218, s[44:45]
	v_pk_fma_f32 v[144:145], v[184:185], v[110:111], v[144:145] op_sel_hi:[1,0,1]
	v_pk_fma_f32 v[146:147], v[186:187], v[110:111], v[146:147] op_sel_hi:[1,0,1]
	v_pk_fma_f32 v[148:149], v[188:189], v[110:111], v[148:149] op_sel_hi:[1,0,1]
	v_pk_fma_f32 v[150:151], v[190:191], v[110:111], v[150:151] op_sel_hi:[1,0,1]
	v_pk_fma_f32 v[152:153], v[192:193], v[110:111], v[152:153] op_sel_hi:[1,0,1]
	v_pk_fma_f32 v[154:155], v[194:195], v[110:111], v[154:155] op_sel_hi:[1,0,1]
	v_pk_fma_f32 v[156:157], v[196:197], v[110:111], v[156:157] op_sel_hi:[1,0,1]
	v_pk_fma_f32 v[158:159], v[198:199], v[110:111], v[158:159] op_sel_hi:[1,0,1]
	s_waitcnt vmcnt(15)
	v_cvt_pk_f32_fp8_e32 v[184:185], v60
	v_cvt_pk_f32_fp8_sdwa v[186:187], v60 src0_sel:WORD_1
	v_cvt_pk_f32_fp8_e32 v[188:189], v61
	v_cvt_pk_f32_fp8_sdwa v[190:191], v61 src0_sel:WORD_1
	v_cvt_pk_f32_fp8_e32 v[192:193], v62
	v_cvt_pk_f32_fp8_sdwa v[194:195], v62 src0_sel:WORD_1
	v_cvt_pk_f32_fp8_e32 v[196:197], v63
	v_cvt_pk_f32_fp8_sdwa v[198:199], v63 src0_sel:WORD_1
	v_or_b32_e32 v218, v95, v203
	global_load_dwordx4 v[60:63], v218, s[44:45]
	v_pk_fma_f32 v[144:145], v[184:185], v[110:111], v[144:145] op_sel:[0,1,0] op_sel_hi:[1,1,1]
	v_pk_fma_f32 v[146:147], v[186:187], v[110:111], v[146:147] op_sel:[0,1,0] op_sel_hi:[1,1,1]
	v_pk_fma_f32 v[148:149], v[188:189], v[110:111], v[148:149] op_sel:[0,1,0] op_sel_hi:[1,1,1]
	v_pk_fma_f32 v[150:151], v[190:191], v[110:111], v[150:151] op_sel:[0,1,0] op_sel_hi:[1,1,1]
	v_pk_fma_f32 v[152:153], v[192:193], v[110:111], v[152:153] op_sel:[0,1,0] op_sel_hi:[1,1,1]
	v_pk_fma_f32 v[154:155], v[194:195], v[110:111], v[154:155] op_sel:[0,1,0] op_sel_hi:[1,1,1]
	v_pk_fma_f32 v[156:157], v[196:197], v[110:111], v[156:157] op_sel:[0,1,0] op_sel_hi:[1,1,1]
	v_pk_fma_f32 v[158:159], v[198:199], v[110:111], v[158:159] op_sel:[0,1,0] op_sel_hi:[1,1,1]
	s_waitcnt vmcnt(15)
	v_cvt_pk_f32_fp8_e32 v[184:185], v0
	v_cvt_pk_f32_fp8_sdwa v[186:187], v0 src0_sel:WORD_1
	v_cvt_pk_f32_fp8_e32 v[188:189], v1
	v_cvt_pk_f32_fp8_sdwa v[190:191], v1 src0_sel:WORD_1
	v_cvt_pk_f32_fp8_e32 v[192:193], v2
	v_cvt_pk_f32_fp8_sdwa v[194:195], v2 src0_sel:WORD_1
	v_cvt_pk_f32_fp8_e32 v[196:197], v3
	v_cvt_pk_f32_fp8_sdwa v[198:199], v3 src0_sel:WORD_1
	v_pk_fma_f32 v[144:145], v[184:185], v[112:113], v[144:145] op_sel_hi:[1,0,1]
	v_pk_fma_f32 v[146:147], v[186:187], v[112:113], v[146:147] op_sel_hi:[1,0,1]
	v_pk_fma_f32 v[148:149], v[188:189], v[112:113], v[148:149] op_sel_hi:[1,0,1]
	v_pk_fma_f32 v[150:151], v[190:191], v[112:113], v[150:151] op_sel_hi:[1,0,1]
	v_pk_fma_f32 v[152:153], v[192:193], v[112:113], v[152:153] op_sel_hi:[1,0,1]
	v_pk_fma_f32 v[154:155], v[194:195], v[112:113], v[154:155] op_sel_hi:[1,0,1]
	v_pk_fma_f32 v[156:157], v[196:197], v[112:113], v[156:157] op_sel_hi:[1,0,1]
	v_pk_fma_f32 v[158:159], v[198:199], v[112:113], v[158:159] op_sel_hi:[1,0,1]
	s_waitcnt vmcnt(14)
	v_cvt_pk_f32_fp8_e32 v[184:185], v4
	v_cvt_pk_f32_fp8_sdwa v[186:187], v4 src0_sel:WORD_1
	v_cvt_pk_f32_fp8_e32 v[188:189], v5
	v_cvt_pk_f32_fp8_sdwa v[190:191], v5 src0_sel:WORD_1
	v_cvt_pk_f32_fp8_e32 v[192:193], v6
	v_cvt_pk_f32_fp8_sdwa v[194:195], v6 src0_sel:WORD_1
	v_cvt_pk_f32_fp8_e32 v[196:197], v7
	v_cvt_pk_f32_fp8_sdwa v[198:199], v7 src0_sel:WORD_1
	v_pk_fma_f32 v[144:145], v[184:185], v[112:113], v[144:145] op_sel:[0,1,0] op_sel_hi:[1,1,1]
	v_pk_fma_f32 v[146:147], v[186:187], v[112:113], v[146:147] op_sel:[0,1,0] op_sel_hi:[1,1,1]
	v_pk_fma_f32 v[148:149], v[188:189], v[112:113], v[148:149] op_sel:[0,1,0] op_sel_hi:[1,1,1]
	v_pk_fma_f32 v[150:151], v[190:191], v[112:113], v[150:151] op_sel:[0,1,0] op_sel_hi:[1,1,1]
	v_pk_fma_f32 v[152:153], v[192:193], v[112:113], v[152:153] op_sel:[0,1,0] op_sel_hi:[1,1,1]
	v_pk_fma_f32 v[154:155], v[194:195], v[112:113], v[154:155] op_sel:[0,1,0] op_sel_hi:[1,1,1]
	v_pk_fma_f32 v[156:157], v[196:197], v[112:113], v[156:157] op_sel:[0,1,0] op_sel_hi:[1,1,1]
	v_pk_fma_f32 v[158:159], v[198:199], v[112:113], v[158:159] op_sel:[0,1,0] op_sel_hi:[1,1,1]
	s_waitcnt vmcnt(13)
; #define LAS __attribute__((address_space(3)))
; template <int Q> __device__ __forceinline__ void s9_pv(const unsigned (&vv)[8], LAS const float* ptw, int half, f32x2_t& oa, f32x2_t& ob) {
; #pragma unroll
;     for (int u2 = 0; u2 < 8; ++u2) { const float p = ptw[2 * (Q * 8 + u2) + half];
;         oa = __builtin_amdgcn_cvt_pk_f32_fp8((int)vv[u2], false) * p + oa; ob = __builtin_amdgcn_cvt_pk_f32_fp8((int)vv[u2], true) * p + ob; }
; }
	v_cvt_pk_f32_fp8_e32 v[184:185], v8
	v_cvt_pk_f32_fp8_sdwa v[186:187], v8 src0_sel:WORD_1
	v_cvt_pk_f32_fp8_e32 v[188:189], v9
	v_cvt_pk_f32_fp8_sdwa v[190:191], v9 src0_sel:WORD_1
	v_cvt_pk_f32_fp8_e32 v[192:193], v10
	v_cvt_pk_f32_fp8_sdwa v[194:195], v10 src0_sel:WORD_1
	v_cvt_pk_f32_fp8_e32 v[196:197], v11
	v_cvt_pk_f32_fp8_sdwa v[198:199], v11 src0_sel:WORD_1
	v_pk_fma_f32 v[144:145], v[184:185], v[114:115], v[144:145] op_sel_hi:[1,0,1]
	v_pk_fma_f32 v[146:147], v[186:187], v[114:115], v[146:147] op_sel_hi:[1,0,1]
	v_pk_fma_f32 v[148:149], v[188:189], v[114:115], v[148:149] op_sel_hi:[1,0,1]
	v_pk_fma_f32 v[150:151], v[190:191], v[114:115], v[150:151] op_sel_hi:[1,0,1]
	v_pk_fma_f32 v[152:153], v[192:193], v[114:115], v[152:153] op_sel_hi:[1,0,1]
	v_pk_fma_f32 v[154:155], v[194:195], v[114:115], v[154:155] op_sel_hi:[1,0,1]
	v_pk_fma_f32 v[156:157], v[196:197], v[114:115], v[156:157] op_sel_hi:[1,0,1]
	v_pk_fma_f32 v[158:159], v[198:199], v[114:115], v[158:159] op_sel_hi:[1,0,1]
	s_waitcnt vmcnt(12)
	v_cvt_pk_f32_fp8_e32 v[184:185], v12
	v_cvt_pk_f32_fp8_sdwa v[186:187], v12 src0_sel:WORD_1
	v_cvt_pk_f32_fp8_e32 v[188:189], v13
	v_cvt_pk_f32_fp8_sdwa v[190:191], v13 src0_sel:WORD_1
	v_cvt_pk_f32_fp8_e32 v[192:193], v14
	v_cvt_pk_f32_fp8_sdwa v[194:195], v14 src0_sel:WORD_1
	v_cvt_pk_f32_fp8_e32 v[196:197], v15
	v_cvt_pk_f32_fp8_sdwa v[198:199], v15 src0_sel:WORD_1
	v_pk_fma_f32 v[144:145], v[184:185], v[114:115], v[144:145] op_sel:[0,1,0] op_sel_hi:[1,1,1]
	v_pk_fma_f32 v[146:147], v[186:187], v[114:115], v[146:147] op_sel:[0,1,0] op_sel_hi:[1,1,1]
	v_pk_fma_f32 v[148:149], v[188:189], v[114:115], v[148:149] op_sel:[0,1,0] op_sel_hi:[1,1,1]
	v_pk_fma_f32 v[150:151], v[190:191], v[114:115], v[150:151] op_sel:[0,1,0] op_sel_hi:[1,1,1]
	v_pk_fma_f32 v[152:153], v[192:193], v[114:115], v[152:153] op_sel:[0,1,0] op_sel_hi:[1,1,1]
	v_pk_fma_f32 v[154:155], v[194:195], v[114:115], v[154:155] op_sel:[0,1,0] op_sel_hi:[1,1,1]
	v_pk_fma_f32 v[156:157], v[196:197], v[114:115], v[156:157] op_sel:[0,1,0] op_sel_hi:[1,1,1]
	v_pk_fma_f32 v[158:159], v[198:199], v[114:115], v[158:159] op_sel:[0,1,0] op_sel_hi:[1,1,1]
	s_waitcnt vmcnt(11)
	v_cvt_pk_f32_fp8_e32 v[184:185], v16
	v_cvt_pk_f32_fp8_sdwa v[186:187], v16 src0_sel:WORD_1
	v_cvt_pk_f32_fp8_e32 v[188:189], v17
	v_cvt_pk_f32_fp8_sdwa v[190:191], v17 src0_sel:WORD_1
	v_cvt_pk_f32_fp8_e32 v[192:193], v18
	v_cvt_pk_f32_fp8_sdwa v[194:195], v18 src0_sel:WORD_1
	v_cvt_pk_f32_fp8_e32 v[196:197], v19
	v_cvt_pk_f32_fp8_sdwa v[198:199], v19 src0_sel:WORD_1
	v_pk_fma_f32 v[144:145], v[184:185], v[116:117], v[144:145] op_sel_hi:[1,0,1]
	v_pk_fma_f32 v[146:147], v[186:187], v[116:117], v[146:147] op_sel_hi:[1,0,1]
	v_pk_fma_f32 v[148:149], v[188:189], v[116:117], v[148:149] op_sel_hi:[1,0,1]
	v_pk_fma_f32 v[150:151], v[190:191], v[116:117], v[150:151] op_sel_hi:[1,0,1]
	v_pk_fma_f32 v[152:153], v[192:193], v[116:117], v[152:153] op_sel_hi:[1,0,1]
	v_pk_fma_f32 v[154:155], v[194:195], v[116:117], v[154:155] op_sel_hi:[1,0,1]
	v_pk_fma_f32 v[156:157], v[196:197], v[116:117], v[156:157] op_sel_hi:[1,0,1]
	v_pk_fma_f32 v[158:159], v[198:199], v[116:117], v[158:159] op_sel_hi:[1,0,1]
	s_waitcnt vmcnt(10)
	v_cvt_pk_f32_fp8_e32 v[184:185], v20
	v_cvt_pk_f32_fp8_sdwa v[186:187], v20 src0_sel:WORD_1
	v_cvt_pk_f32_fp8_e32 v[188:189], v21
	v_cvt_pk_f32_fp8_sdwa v[190:191], v21 src0_sel:WORD_1
	v_cvt_pk_f32_fp8_e32 v[192:193], v22
	v_cvt_pk_f32_fp8_sdwa v[194:195], v22 src0_sel:WORD_1
	v_cvt_pk_f32_fp8_e32 v[196:197], v23
	v_cvt_pk_f32_fp8_sdwa v[198:199], v23 src0_sel:WORD_1
	v_pk_fma_f32 v[144:145], v[184:185], v[116:117], v[144:145] op_sel:[0,1,0] op_sel_hi:[1,1,1]
	v_pk_fma_f32 v[146:147], v[186:187], v[116:117], v[146:147] op_sel:[0,1,0] op_sel_hi:[1,1,1]
	v_pk_fma_f32 v[148:149], v[188:189], v[116:117], v[148:149] op_sel:[0,1,0] op_sel_hi:[1,1,1]
	v_pk_fma_f32 v[150:151], v[190:191], v[116:117], v[150:151] op_sel:[0,1,0] op_sel_hi:[1,1,1]
	v_pk_fma_f32 v[152:153], v[192:193], v[116:117], v[152:153] op_sel:[0,1,0] op_sel_hi:[1,1,1]
	v_pk_fma_f32 v[154:155], v[194:195], v[116:117], v[154:155] op_sel:[0,1,0] op_sel_hi:[1,1,1]
	v_pk_fma_f32 v[156:157], v[196:197], v[116:117], v[156:157] op_sel:[0,1,0] op_sel_hi:[1,1,1]
	v_pk_fma_f32 v[158:159], v[198:199], v[116:117], v[158:159] op_sel:[0,1,0] op_sel_hi:[1,1,1]
	s_waitcnt vmcnt(9)
	v_cvt_pk_f32_fp8_e32 v[184:185], v24
	v_cvt_pk_f32_fp8_sdwa v[186:187], v24 src0_sel:WORD_1
	v_cvt_pk_f32_fp8_e32 v[188:189], v25
	v_cvt_pk_f32_fp8_sdwa v[190:191], v25 src0_sel:WORD_1
	v_cvt_pk_f32_fp8_e32 v[192:193], v26
	v_cvt_pk_f32_fp8_sdwa v[194:195], v26 src0_sel:WORD_1
	v_cvt_pk_f32_fp8_e32 v[196:197], v27
	v_cvt_pk_f32_fp8_sdwa v[198:199], v27 src0_sel:WORD_1
	v_pk_fma_f32 v[144:145], v[184:185], v[118:119], v[144:145] op_sel_hi:[1,0,1]
	v_pk_fma_f32 v[146:147], v[186:187], v[118:119], v[146:147] op_sel_hi:[1,0,1]
	v_pk_fma_f32 v[148:149], v[188:189], v[118:119], v[148:149] op_sel_hi:[1,0,1]
	v_pk_fma_f32 v[150:151], v[190:191], v[118:119], v[150:151] op_sel_hi:[1,0,1]
	v_pk_fma_f32 v[152:153], v[192:193], v[118:119], v[152:153] op_sel_hi:[1,0,1]
	v_pk_fma_f32 v[154:155], v[194:195], v[118:119], v[154:155] op_sel_hi:[1,0,1]
	v_pk_fma_f32 v[156:157], v[196:197], v[118:119], v[156:157] op_sel_hi:[1,0,1]
	v_pk_fma_f32 v[158:159], v[198:199], v[118:119], v[158:159] op_sel_hi:[1,0,1]
	s_waitcnt vmcnt(8)
; #define LAS __attribute__((address_space(3)))
; template <int Q> __device__ __forceinline__ void s9_pv(const unsigned (&vv)[8], LAS const float* ptw, int half, f32x2_t& oa, f32x2_t& ob) {
; #pragma unroll
;     for (int u2 = 0; u2 < 8; ++u2) { const float p = ptw[2 * (Q * 8 + u2) + half];
;         oa = __builtin_amdgcn_cvt_pk_f32_fp8((int)vv[u2], false) * p + oa; ob = __builtin_amdgcn_cvt_pk_f32_fp8((int)vv[u2], true) * p + ob; }
; }
	v_cvt_pk_f32_fp8_e32 v[184:185], v28
	v_cvt_pk_f32_fp8_sdwa v[186:187], v28 src0_sel:WORD_1
	v_cvt_pk_f32_fp8_e32 v[188:189], v29
	v_cvt_pk_f32_fp8_sdwa v[190:191], v29 src0_sel:WORD_1
	v_cvt_pk_f32_fp8_e32 v[192:193], v30
	v_cvt_pk_f32_fp8_sdwa v[194:195], v30 src0_sel:WORD_1
	v_cvt_pk_f32_fp8_e32 v[196:197], v31
	v_cvt_pk_f32_fp8_sdwa v[198:199], v31 src0_sel:WORD_1
	v_pk_fma_f32 v[144:145], v[184:185], v[118:119], v[144:145] op_sel:[0,1,0] op_sel_hi:[1,1,1]
	v_pk_fma_f32 v[146:147], v[186:187], v[118:119], v[146:147] op_sel:[0,1,0] op_sel_hi:[1,1,1]
	v_pk_fma_f32 v[148:149], v[188:189], v[118:119], v[148:149] op_sel:[0,1,0] op_sel_hi:[1,1,1]
	v_pk_fma_f32 v[150:151], v[190:191], v[118:119], v[150:151] op_sel:[0,1,0] op_sel_hi:[1,1,1]
	v_pk_fma_f32 v[152:153], v[192:193], v[118:119], v[152:153] op_sel:[0,1,0] op_sel_hi:[1,1,1]
	v_pk_fma_f32 v[154:155], v[194:195], v[118:119], v[154:155] op_sel:[0,1,0] op_sel_hi:[1,1,1]
	v_pk_fma_f32 v[156:157], v[196:197], v[118:119], v[156:157] op_sel:[0,1,0] op_sel_hi:[1,1,1]
	v_pk_fma_f32 v[158:159], v[198:199], v[118:119], v[158:159] op_sel:[0,1,0] op_sel_hi:[1,1,1]
	s_waitcnt vmcnt(7)
	v_cvt_pk_f32_fp8_e32 v[184:185], v32
	v_cvt_pk_f32_fp8_sdwa v[186:187], v32 src0_sel:WORD_1
	v_cvt_pk_f32_fp8_e32 v[188:189], v33
	v_cvt_pk_f32_fp8_sdwa v[190:191], v33 src0_sel:WORD_1
	v_cvt_pk_f32_fp8_e32 v[192:193], v34
	v_cvt_pk_f32_fp8_sdwa v[194:195], v34 src0_sel:WORD_1
	v_cvt_pk_f32_fp8_e32 v[196:197], v35
	v_cvt_pk_f32_fp8_sdwa v[198:199], v35 src0_sel:WORD_1
	v_pk_fma_f32 v[144:145], v[184:185], v[120:121], v[144:145] op_sel_hi:[1,0,1]
	v_pk_fma_f32 v[146:147], v[186:187], v[120:121], v[146:147] op_sel_hi:[1,0,1]
	v_pk_fma_f32 v[148:149], v[188:189], v[120:121], v[148:149] op_sel_hi:[1,0,1]
	v_pk_fma_f32 v[150:151], v[190:191], v[120:121], v[150:151] op_sel_hi:[1,0,1]
	v_pk_fma_f32 v[152:153], v[192:193], v[120:121], v[152:153] op_sel_hi:[1,0,1]
	v_pk_fma_f32 v[154:155], v[194:195], v[120:121], v[154:155] op_sel_hi:[1,0,1]
	v_pk_fma_f32 v[156:157], v[196:197], v[120:121], v[156:157] op_sel_hi:[1,0,1]
	v_pk_fma_f32 v[158:159], v[198:199], v[120:121], v[158:159] op_sel_hi:[1,0,1]
	s_waitcnt vmcnt(6)
	v_cvt_pk_f32_fp8_e32 v[184:185], v36
	v_cvt_pk_f32_fp8_sdwa v[186:187], v36 src0_sel:WORD_1
	v_cvt_pk_f32_fp8_e32 v[188:189], v37
	v_cvt_pk_f32_fp8_sdwa v[190:191], v37 src0_sel:WORD_1
	v_cvt_pk_f32_fp8_e32 v[192:193], v38
	v_cvt_pk_f32_fp8_sdwa v[194:195], v38 src0_sel:WORD_1
	v_cvt_pk_f32_fp8_e32 v[196:197], v39
	v_cvt_pk_f32_fp8_sdwa v[198:199], v39 src0_sel:WORD_1
	v_pk_fma_f32 v[144:145], v[184:185], v[120:121], v[144:145] op_sel:[0,1,0] op_sel_hi:[1,1,1]
	v_pk_fma_f32 v[146:147], v[186:187], v[120:121], v[146:147] op_sel:[0,1,0] op_sel_hi:[1,1,1]
	v_pk_fma_f32 v[148:149], v[188:189], v[120:121], v[148:149] op_sel:[0,1,0] op_sel_hi:[1,1,1]
	v_pk_fma_f32 v[150:151], v[190:191], v[120:121], v[150:151] op_sel:[0,1,0] op_sel_hi:[1,1,1]
	v_pk_fma_f32 v[152:153], v[192:193], v[120:121], v[152:153] op_sel:[0,1,0] op_sel_hi:[1,1,1]
	v_pk_fma_f32 v[154:155], v[194:195], v[120:121], v[154:155] op_sel:[0,1,0] op_sel_hi:[1,1,1]
	v_pk_fma_f32 v[156:157], v[196:197], v[120:121], v[156:157] op_sel:[0,1,0] op_sel_hi:[1,1,1]
	v_pk_fma_f32 v[158:159], v[198:199], v[120:121], v[158:159] op_sel:[0,1,0] op_sel_hi:[1,1,1]
	s_waitcnt vmcnt(5)
	v_cvt_pk_f32_fp8_e32 v[184:185], v40
	v_cvt_pk_f32_fp8_sdwa v[186:187], v40 src0_sel:WORD_1
	v_cvt_pk_f32_fp8_e32 v[188:189], v41
	v_cvt_pk_f32_fp8_sdwa v[190:191], v41 src0_sel:WORD_1
	v_cvt_pk_f32_fp8_e32 v[192:193], v42
	v_cvt_pk_f32_fp8_sdwa v[194:195], v42 src0_sel:WORD_1
	v_cvt_pk_f32_fp8_e32 v[196:197], v43
	v_cvt_pk_f32_fp8_sdwa v[198:199], v43 src0_sel:WORD_1
	v_pk_fma_f32 v[144:145], v[184:185], v[122:123], v[144:145] op_sel_hi:[1,0,1]
	v_pk_fma_f32 v[146:147], v[186:187], v[122:123], v[146:147] op_sel_hi:[1,0,1]
	v_pk_fma_f32 v[148:149], v[188:189], v[122:123], v[148:149] op_sel_hi:[1,0,1]
	v_pk_fma_f32 v[150:151], v[190:191], v[122:123], v[150:151] op_sel_hi:[1,0,1]
	v_pk_fma_f32 v[152:153], v[192:193], v[122:123], v[152:153] op_sel_hi:[1,0,1]
	v_pk_fma_f32 v[154:155], v[194:195], v[122:123], v[154:155] op_sel_hi:[1,0,1]
	v_pk_fma_f32 v[156:157], v[196:197], v[122:123], v[156:157] op_sel_hi:[1,0,1]
	v_pk_fma_f32 v[158:159], v[198:199], v[122:123], v[158:159] op_sel_hi:[1,0,1]
	s_waitcnt vmcnt(4)
	v_cvt_pk_f32_fp8_e32 v[184:185], v44
	v_cvt_pk_f32_fp8_sdwa v[186:187], v44 src0_sel:WORD_1
	v_cvt_pk_f32_fp8_e32 v[188:189], v45
	v_cvt_pk_f32_fp8_sdwa v[190:191], v45 src0_sel:WORD_1
	v_cvt_pk_f32_fp8_e32 v[192:193], v46
	v_cvt_pk_f32_fp8_sdwa v[194:195], v46 src0_sel:WORD_1
	v_cvt_pk_f32_fp8_e32 v[196:197], v47
	v_cvt_pk_f32_fp8_sdwa v[198:199], v47 src0_sel:WORD_1
	v_pk_fma_f32 v[144:145], v[184:185], v[122:123], v[144:145] op_sel:[0,1,0] op_sel_hi:[1,1,1]
	v_pk_fma_f32 v[146:147], v[186:187], v[122:123], v[146:147] op_sel:[0,1,0] op_sel_hi:[1,1,1]
	v_pk_fma_f32 v[148:149], v[188:189], v[122:123], v[148:149] op_sel:[0,1,0] op_sel_hi:[1,1,1]
	v_pk_fma_f32 v[150:151], v[190:191], v[122:123], v[150:151] op_sel:[0,1,0] op_sel_hi:[1,1,1]
	v_pk_fma_f32 v[152:153], v[192:193], v[122:123], v[152:153] op_sel:[0,1,0] op_sel_hi:[1,1,1]
	v_pk_fma_f32 v[154:155], v[194:195], v[122:123], v[154:155] op_sel:[0,1,0] op_sel_hi:[1,1,1]
	v_pk_fma_f32 v[156:157], v[196:197], v[122:123], v[156:157] op_sel:[0,1,0] op_sel_hi:[1,1,1]
	v_pk_fma_f32 v[158:159], v[198:199], v[122:123], v[158:159] op_sel:[0,1,0] op_sel_hi:[1,1,1]
	s_waitcnt vmcnt(3)
; #define LAS __attribute__((address_space(3)))
; template <int Q> __device__ __forceinline__ void s9_pv(const unsigned (&vv)[8], LAS const float* ptw, int half, f32x2_t& oa, f32x2_t& ob) {
; #pragma unroll
;     for (int u2 = 0; u2 < 8; ++u2) { const float p = ptw[2 * (Q * 8 + u2) + half];
;         oa = __builtin_amdgcn_cvt_pk_f32_fp8((int)vv[u2], false) * p + oa; ob = __builtin_amdgcn_cvt_pk_f32_fp8((int)vv[u2], true) * p + ob; }
; }
	v_cvt_pk_f32_fp8_e32 v[184:185], v48
	v_cvt_pk_f32_fp8_sdwa v[186:187], v48 src0_sel:WORD_1
	v_cvt_pk_f32_fp8_e32 v[188:189], v49
	v_cvt_pk_f32_fp8_sdwa v[190:191], v49 src0_sel:WORD_1
	v_cvt_pk_f32_fp8_e32 v[192:193], v50
	v_cvt_pk_f32_fp8_sdwa v[194:195], v50 src0_sel:WORD_1
	v_cvt_pk_f32_fp8_e32 v[196:197], v51
	v_cvt_pk_f32_fp8_sdwa v[198:199], v51 src0_sel:WORD_1
	v_pk_fma_f32 v[144:145], v[184:185], v[124:125], v[144:145] op_sel_hi:[1,0,1]
	v_pk_fma_f32 v[146:147], v[186:187], v[124:125], v[146:147] op_sel_hi:[1,0,1]
	v_pk_fma_f32 v[148:149], v[188:189], v[124:125], v[148:149] op_sel_hi:[1,0,1]
	v_pk_fma_f32 v[150:151], v[190:191], v[124:125], v[150:151] op_sel_hi:[1,0,1]
	v_pk_fma_f32 v[152:153], v[192:193], v[124:125], v[152:153] op_sel_hi:[1,0,1]
	v_pk_fma_f32 v[154:155], v[194:195], v[124:125], v[154:155] op_sel_hi:[1,0,1]
	v_pk_fma_f32 v[156:157], v[196:197], v[124:125], v[156:157] op_sel_hi:[1,0,1]
	v_pk_fma_f32 v[158:159], v[198:199], v[124:125], v[158:159] op_sel_hi:[1,0,1]
	s_waitcnt vmcnt(2)
	v_cvt_pk_f32_fp8_e32 v[184:185], v52
	v_cvt_pk_f32_fp8_sdwa v[186:187], v52 src0_sel:WORD_1
	v_cvt_pk_f32_fp8_e32 v[188:189], v53
	v_cvt_pk_f32_fp8_sdwa v[190:191], v53 src0_sel:WORD_1
	v_cvt_pk_f32_fp8_e32 v[192:193], v54
	v_cvt_pk_f32_fp8_sdwa v[194:195], v54 src0_sel:WORD_1
	v_cvt_pk_f32_fp8_e32 v[196:197], v55
	v_cvt_pk_f32_fp8_sdwa v[198:199], v55 src0_sel:WORD_1
	v_pk_fma_f32 v[144:145], v[184:185], v[124:125], v[144:145] op_sel:[0,1,0] op_sel_hi:[1,1,1]
	v_pk_fma_f32 v[146:147], v[186:187], v[124:125], v[146:147] op_sel:[0,1,0] op_sel_hi:[1,1,1]
	v_pk_fma_f32 v[148:149], v[188:189], v[124:125], v[148:149] op_sel:[0,1,0] op_sel_hi:[1,1,1]
	v_pk_fma_f32 v[150:151], v[190:191], v[124:125], v[150:151] op_sel:[0,1,0] op_sel_hi:[1,1,1]
	v_pk_fma_f32 v[152:153], v[192:193], v[124:125], v[152:153] op_sel:[0,1,0] op_sel_hi:[1,1,1]
	v_pk_fma_f32 v[154:155], v[194:195], v[124:125], v[154:155] op_sel:[0,1,0] op_sel_hi:[1,1,1]
	v_pk_fma_f32 v[156:157], v[196:197], v[124:125], v[156:157] op_sel:[0,1,0] op_sel_hi:[1,1,1]
	v_pk_fma_f32 v[158:159], v[198:199], v[124:125], v[158:159] op_sel:[0,1,0] op_sel_hi:[1,1,1]
	s_waitcnt vmcnt(1)
	v_cvt_pk_f32_fp8_e32 v[184:185], v56
	v_cvt_pk_f32_fp8_sdwa v[186:187], v56 src0_sel:WORD_1
	v_cvt_pk_f32_fp8_e32 v[188:189], v57
	v_cvt_pk_f32_fp8_sdwa v[190:191], v57 src0_sel:WORD_1
	v_cvt_pk_f32_fp8_e32 v[192:193], v58
	v_cvt_pk_f32_fp8_sdwa v[194:195], v58 src0_sel:WORD_1
	v_cvt_pk_f32_fp8_e32 v[196:197], v59
	v_cvt_pk_f32_fp8_sdwa v[198:199], v59 src0_sel:WORD_1
	v_pk_fma_f32 v[144:145], v[184:185], v[126:127], v[144:145] op_sel_hi:[1,0,1]
	v_pk_fma_f32 v[146:147], v[186:187], v[126:127], v[146:147] op_sel_hi:[1,0,1]
	v_pk_fma_f32 v[148:149], v[188:189], v[126:127], v[148:149] op_sel_hi:[1,0,1]
	v_pk_fma_f32 v[150:151], v[190:191], v[126:127], v[150:151] op_sel_hi:[1,0,1]
	v_pk_fma_f32 v[152:153], v[192:193], v[126:127], v[152:153] op_sel_hi:[1,0,1]
	v_pk_fma_f32 v[154:155], v[194:195], v[126:127], v[154:155] op_sel_hi:[1,0,1]
	v_pk_fma_f32 v[156:157], v[196:197], v[126:127], v[156:157] op_sel_hi:[1,0,1]
	v_pk_fma_f32 v[158:159], v[198:199], v[126:127], v[158:159] op_sel_hi:[1,0,1]
	s_waitcnt vmcnt(0)
; __device__ __forceinline__ unsigned pk2(float lo, float hi) { return f2bf(lo) | (f2bf(hi) << 16); }
; __device__ __forceinline__ float swap32_sum(float a, float b) { unsigned x, y; pl32(__builtin_bit_cast(unsigned, a), __builtin_bit_cast(unsigned, b), x, y); return __builtin_bit_cast(float, x) + __builtin_bit_cast(float, y); }
; __device__ __forceinline__ void sparse_unit7(const bf16_t* QKV, const unsigned char* K8, const unsigned char* V8, const int (&selv)[4], bf16_t* OB, LAS unsigned char* wl, int t, int h, int lane) {
;     ...
;     const float inv = 1.f / wave_sum(l);
;     const float r0 = swap32_sum(oa.x, oa.x), r1 = swap32_sum(oa.y, oa.y), r2 = swap32_sum(ob.x, ob.x), r3 = swap32_sum(ob.y, ob.y);
;     if (half == 0) { u32x2 o; o.x = pk2(r0 * inv, r1 * inv); o.y = pk2(r2 * inv, r3 * inv); *(u32x2*)(OB + (size_t)t * 1024 + h * 128 + l4) = o; }
; __global__ void __launch_bounds__(NTHREADS, 2) mega(Args a) {
;     ...
;                     for (int t = qg; t < SEQ; t += nqg) { int selc[4];
; #pragma unroll
;                         for (int s = 0; s < 4; ++s) selc[s] = seln[s];
;                         const int tn = min(t + nqg, SEQ - 1);
; #pragma unroll
;                         for (int s = 0; s < 4; ++s) seln[s] = (int)SEL[(size_t)tn * 256 + 64 * s + lane];
;                         sparse_unit7(QKV, K8, V8, selc, OB, lds + wave * 4096, t, h, lane); } }
	v_cvt_pk_f32_fp8_e32 v[184:185], v60
	v_cvt_pk_f32_fp8_sdwa v[186:187], v60 src0_sel:WORD_1
	v_cvt_pk_f32_fp8_e32 v[188:189], v61
	v_cvt_pk_f32_fp8_sdwa v[190:191], v61 src0_sel:WORD_1
	v_cvt_pk_f32_fp8_e32 v[192:193], v62
	v_cvt_pk_f32_fp8_sdwa v[194:195], v62 src0_sel:WORD_1
	v_cvt_pk_f32_fp8_e32 v[196:197], v63
	v_cvt_pk_f32_fp8_sdwa v[198:199], v63 src0_sel:WORD_1
	v_pk_fma_f32 v[144:145], v[184:185], v[126:127], v[144:145] op_sel:[0,1,0] op_sel_hi:[1,1,1]
	v_pk_fma_f32 v[146:147], v[186:187], v[126:127], v[146:147] op_sel:[0,1,0] op_sel_hi:[1,1,1]
	v_pk_fma_f32 v[148:149], v[188:189], v[126:127], v[148:149] op_sel:[0,1,0] op_sel_hi:[1,1,1]
	v_pk_fma_f32 v[150:151], v[190:191], v[126:127], v[150:151] op_sel:[0,1,0] op_sel_hi:[1,1,1]
	v_pk_fma_f32 v[152:153], v[192:193], v[126:127], v[152:153] op_sel:[0,1,0] op_sel_hi:[1,1,1]
	v_pk_fma_f32 v[154:155], v[194:195], v[126:127], v[154:155] op_sel:[0,1,0] op_sel_hi:[1,1,1]
	v_pk_fma_f32 v[156:157], v[196:197], v[126:127], v[156:157] op_sel:[0,1,0] op_sel_hi:[1,1,1]
	v_pk_fma_f32 v[158:159], v[198:199], v[126:127], v[158:159] op_sel:[0,1,0] op_sel_hi:[1,1,1]
	v_rcp_f32_e32 v218, v246
	s_nop 1
	v_fma_f32 v219, -v246, v218, 1.0
	v_fma_f32 v218, v219, v218, v218
	v_add_f32_dpp v144, v144, v144 row_ror:8 row_mask:0xf bank_mask:0xf bound_ctrl:1
	v_add_f32_dpp v145, v145, v145 row_ror:8 row_mask:0xf bank_mask:0xf bound_ctrl:1
	v_add_f32_dpp v146, v146, v146 row_ror:8 row_mask:0xf bank_mask:0xf bound_ctrl:1
	v_add_f32_dpp v147, v147, v147 row_ror:8 row_mask:0xf bank_mask:0xf bound_ctrl:1
	v_add_f32_dpp v148, v148, v148 row_ror:8 row_mask:0xf bank_mask:0xf bound_ctrl:1
	v_add_f32_dpp v149, v149, v149 row_ror:8 row_mask:0xf bank_mask:0xf bound_ctrl:1
	v_add_f32_dpp v150, v150, v150 row_ror:8 row_mask:0xf bank_mask:0xf bound_ctrl:1
	v_add_f32_dpp v151, v151, v151 row_ror:8 row_mask:0xf bank_mask:0xf bound_ctrl:1
	v_add_f32_dpp v152, v152, v152 row_ror:8 row_mask:0xf bank_mask:0xf bound_ctrl:1
	v_add_f32_dpp v153, v153, v153 row_ror:8 row_mask:0xf bank_mask:0xf bound_ctrl:1
	v_add_f32_dpp v154, v154, v154 row_ror:8 row_mask:0xf bank_mask:0xf bound_ctrl:1
	v_add_f32_dpp v155, v155, v155 row_ror:8 row_mask:0xf bank_mask:0xf bound_ctrl:1
	v_add_f32_dpp v156, v156, v156 row_ror:8 row_mask:0xf bank_mask:0xf bound_ctrl:1
	v_add_f32_dpp v157, v157, v157 row_ror:8 row_mask:0xf bank_mask:0xf bound_ctrl:1
	v_add_f32_dpp v158, v158, v158 row_ror:8 row_mask:0xf bank_mask:0xf bound_ctrl:1
	v_add_f32_dpp v159, v159, v159 row_ror:8 row_mask:0xf bank_mask:0xf bound_ctrl:1
	s_nop 1
	v_permlane16_swap_b32_e32 v144, v148
	v_permlane16_swap_b32_e32 v145, v149
	v_permlane16_swap_b32_e32 v146, v150
	v_permlane16_swap_b32_e32 v147, v151
	v_permlane16_swap_b32_e32 v152, v156
	v_permlane16_swap_b32_e32 v153, v157
	v_permlane16_swap_b32_e32 v154, v158
	v_permlane16_swap_b32_e32 v155, v159
	s_nop 1
	v_add_f32_e32 v144, v144, v148
	v_add_f32_e32 v145, v145, v149
	v_add_f32_e32 v146, v146, v150
	v_add_f32_e32 v147, v147, v151
	v_add_f32_e32 v152, v152, v156
	v_add_f32_e32 v153, v153, v157
	v_add_f32_e32 v154, v154, v158
	v_add_f32_e32 v155, v155, v159
	s_nop 1
	v_permlane32_swap_b32_e32 v144, v152
	v_permlane32_swap_b32_e32 v145, v153
	v_permlane32_swap_b32_e32 v146, v154
	v_permlane32_swap_b32_e32 v147, v155
	s_nop 1
	v_add_f32_e32 v144, v144, v152
	v_add_f32_e32 v145, v145, v153
	v_add_f32_e32 v146, v146, v154
	v_add_f32_e32 v147, v147, v155
	v_mul_f32_e32 v144, v144, v218
	v_mul_f32_e32 v145, v145, v218
	v_mul_f32_e32 v146, v146, v218
	v_mul_f32_e32 v147, v147, v218
	v_cvt_pk_bf16_f32 v246, v144, v145
	v_cvt_pk_bf16_f32 v247, v146, v147
	s_lshl_b32 s0, s34, 11
	s_add_u32 s0, s46, s0
	s_addc_u32 s1, s47, 0
	s_mov_b64 s[4:5], exec
	s_mov_b32 exec_lo, 0x00ff00ff
	s_mov_b32 exec_hi, 0x00ff00ff
	global_store_dwordx2 v215, v[246:247], s[0:1]
	s_mov_b64 exec, s[4:5]
	s_add_i32 s34, s34, s48
	s_cmpk_lt_i32 s34, 0x4000
	s_cbranch_scc1 .Lsp_unit
	s_waitcnt vmcnt(0)
	s_branch .LBB0_190

; __device__ __forceinline__ void dilated_block(const bf16_t* QKV, bf16_t* OG, float* LSE, LAS unsigned char* lds, int u, int tid) {
;     const int lane = tid & 63, wave = __builtin_amdgcn_readfirstlane(tid >> 6), n16 = lane & 15, slab = lane >> 4;
;     const int g = u >> 9, rem = u & 511, hs = rem >> 7, pn = rem & 127;
;     const int rsh = 2 * g, nbk = 128 >> rsh, p = pn >> (7 - rsh), nb = pn & (nbk - 1);
;     const int head = g * 4 + hs, mbase = 128 * (nb - 1);
;     __syncthreads();
; #pragma unroll
;     for (int i = 0; i < 8; ++i) { const int c = tid + 512 * i, row = c >> 4, ch = c & 15, m = mbase + row; u32x4 v = {0u, 0u, 0u, 0u};
;         if (m >= 0) v = *(const u32x4*)(QKV + (size_t)((m << rsh) + p) * QKVW + COL_AV + head * 128 + ch * 8);
;         *(LAS u32x4*)(lds + row * VRS + ch * 16) = v; }
;     __syncthreads();
;     const int i0 = wave * 16;
;     const int tq = ((mbase + 128 + i0 + n16) << rsh) + p;
;     bf16x8 qf[4];
; #pragma unroll
;     for (int ks = 0; ks < 4; ++ks) qf[ks] = *(const bf16x8*)(QKV + (size_t)tq * QKVW + COL_AQ + head * 128 + ks * 32 + slab * 8);
;     f32x4 sacc[10];
; #pragma unroll
;     for (int jt = 0; jt < 9; ++jt) { int m = mbase + i0 + 16 * jt + n16; m = max(m, 0);
;         const bf16_t* kp = QKV + (size_t)((m << rsh) + p) * QKVW + COL_AK + head * 128 + slab * 8;
;         f32x4 acc = {0.f, 0.f, 0.f, 0.f};
; #pragma unroll
;         for (int ks = 0; ks < 4; ++ks) acc = __builtin_amdgcn_mfma_f32_16x16x32_bf16(*(const bf16x8*)(kp + ks * 32), qf[ks], acc, 0, 0, 0);
;         sacc[jt] = acc; }
;     float mx = -INFINITY;
; #pragma unroll
;     for (int jt = 0; jt < 9; ++jt)
; #pragma unroll
;         for (int i = 0; i < 4; ++i) { const int d = 128 + n16 - 16 * jt - 4 * slab - i, kk = i0 + 16 * jt + 4 * slab + i;
;             const bool ok = (d >= 0) && (d <= 128) && (nb > 0 || kk >= 128);
;             const float s = ok ? sacc[jt][i] * 0.08838834764831845f : -INFINITY; sacc[jt][i] = s; mx = fmaxf(mx, s); }
;     { unsigned x, y; pl16(__builtin_bit_cast(unsigned, mx), __builtin_bit_cast(unsigned, mx), x, y); mx = fmaxf(__builtin_bit_cast(float, x), __builtin_bit_cast(float, y));
;       pl32(__builtin_bit_cast(unsigned, mx), __builtin_bit_cast(unsigned, mx), x, y); mx = fmaxf(__builtin_bit_cast(float, x), __builtin_bit_cast(float, y)); }
;     float lsum = 0.f;
; #pragma unroll
.LBB0_191:
	s_and_b64 vcc, exec, s[0:1]
	s_cbranch_vccz .LBB0_219
	v_readlane_b32 s0, v250, 31
	s_cmp_gt_i32 s0, 1
	s_mov_b64 s[0:1], -1
	s_cbranch_scc0 .LBB0_1011
	v_readlane_b32 s0, v250, 31
	s_cmp_gt_i32 s0, 2
	s_mov_b64 s[0:1], -1
	s_cbranch_scc0 .LBB0_1004
	v_readlane_b32 s98, v251, 0
	v_readlane_b32 s99, v250, 18
	s_nop 3
	s_lshl_b32 s98, s98, 3
	s_add_i32 s100, s98, s99
	s_mov_b32 s101, s100
	v_lshlrev_b32_e32 v36, 4, v182
	s_lshl_b32 s98, s100, 10
	s_add_u32 s98, s98, 0x3af00000
	v_add_u32_e32 v32, s98, v36
	v_add_u32_e32 v33, 0x1000000, v32
	v_lshrrev_b32_e32 v37, 3, v182
	v_and_b32_e32 v38, 7, v182
	v_lshlrev_b32_e32 v37, 21, v37
	v_lshl_or_b32 v37, v38, 4, v37
	s_lshl_b32 s98, s100, 7
	s_add_u32 s98, s98, 0x3cf00000
	v_add_u32_e32 v34, s98, v37
	v_add_u32_e32 v35, 0x1000000, v34
	s_lshl_b32 s98, s66, 10
	s_lshl_b32 s99, s66, 7
.Lcp_loop:
	s_cmpk_lt_i32 s100, 0x4000
	s_cbranch_scc0 .Lcp_ld_done
	global_load_dwordx4 v[0:3], v32, s[90:91]
	global_load_dwordx4 v[4:7], v33, s[90:91]
	v_add_u32_e32 v32, s98, v32
	v_add_u32_e32 v33, s98, v33
	s_add_i32 s100, s100, s66
	s_cmpk_lt_i32 s100, 0x4000
	s_cbranch_scc0 .Lcp_ld_done
	global_load_dwordx4 v[8:11], v32, s[90:91]
	global_load_dwordx4 v[12:15], v33, s[90:91]
	v_add_u32_e32 v32, s98, v32
	v_add_u32_e32 v33, s98, v33
	s_add_i32 s100, s100, s66
	s_cmpk_lt_i32 s100, 0x4000
	s_cbranch_scc0 .Lcp_ld_done
	global_load_dwordx4 v[16:19], v32, s[90:91]
	global_load_dwordx4 v[20:23], v33, s[90:91]
	v_add_u32_e32 v32, s98, v32
	v_add_u32_e32 v33, s98, v33
	s_add_i32 s100, s100, s66
	s_cmpk_lt_i32 s100, 0x4000
	s_cbranch_scc0 .Lcp_ld_done
	global_load_dwordx4 v[24:27], v32, s[90:91]
	global_load_dwordx4 v[28:31], v33, s[90:91]
	v_add_u32_e32 v32, s98, v32
	v_add_u32_e32 v33, s98, v33
	s_add_i32 s100, s100, s66
.Lcp_ld_done:
	s_waitcnt vmcnt(0)
	s_cmpk_lt_i32 s101, 0x4000
	s_cbranch_scc0 .Lcp_st_done
	global_store_dwordx4 v34, v[0:3], s[90:91]
	global_store_dwordx4 v35, v[4:7], s[90:91]
	s_nop 1
	v_add_u32_e32 v34, s99, v34
	v_add_u32_e32 v35, s99, v35
	s_add_i32 s101, s101, s66
	s_cmpk_lt_i32 s101, 0x4000
	s_cbranch_scc0 .Lcp_st_done
	global_store_dwordx4 v34, v[8:11], s[90:91]
	global_store_dwordx4 v35, v[12:15], s[90:91]
	s_nop 1
	v_add_u32_e32 v34, s99, v34
	v_add_u32_e32 v35, s99, v35
	s_add_i32 s101, s101, s66
	s_cmpk_lt_i32 s101, 0x4000
	s_cbranch_scc0 .Lcp_st_done
	global_store_dwordx4 v34, v[16:19], s[90:91]
	global_store_dwordx4 v35, v[20:23], s[90:91]
	s_nop 1
	v_add_u32_e32 v34, s99, v34
	v_add_u32_e32 v35, s99, v35
	s_add_i32 s101, s101, s66
	s_cmpk_lt_i32 s101, 0x4000
	s_cbranch_scc0 .Lcp_st_done
	global_store_dwordx4 v34, v[24:27], s[90:91]
	global_store_dwordx4 v35, v[28:31], s[90:91]
	s_nop 1
	v_add_u32_e32 v34, s99, v34
	v_add_u32_e32 v35, s99, v35
	s_add_i32 s101, s101, s66
.Lcp_st_done:
	s_cmpk_lt_i32 s101, 0x4000
	s_cbranch_scc1 .Lcp_loop
	v_lshrrev_b32_e32 v0, 4, v182
	v_readlane_b32 s0, v251, 41
	v_lshlrev_b32_e32 v1, 3, v0
	v_readlane_b32 s1, v251, 42
	v_and_b32_e32 v154, 15, v212
	s_waitcnt vmcnt(3)
	v_lshlrev_b32_e32 v49, 2, v0
	s_andn2_b64 vcc, exec, s[0:1]
	v_lshlrev_b32_e32 v160, 1, v1
	s_cbranch_vccnz .LBB0_220
	v_add_u32_e32 v2, 0x200, v212
	v_add_u32_e32 v3, 0x400, v212
	v_add_u32_e32 v4, 0x600, v212
	v_add_u32_e32 v5, 0x800, v212
	v_add_u32_e32 v6, 0xa00, v212
	v_add_u32_e32 v7, 0xc00, v212
	s_waitcnt vmcnt(12)
	v_add_u32_e32 v8, 0xe00, v212
	v_or_b32_e32 v9, 0x80, v154
	v_ashrrev_i32_e32 v51, 4, v212
	s_movk_i32 s0, 0x110
	v_ashrrev_i32_e32 v56, 4, v2
	v_ashrrev_i32_e32 v57, 4, v3
	v_ashrrev_i32_e32 v58, 4, v4
	v_ashrrev_i32_e32 v59, 4, v5
	v_ashrrev_i32_e32 v60, 4, v6
	s_waitcnt vmcnt(2)
	v_ashrrev_i32_e32 v61, 4, v7
	s_waitcnt vmcnt(1)
	v_ashrrev_i32_e32 v62, 4, v8
	v_sub_u32_e32 v10, v9, v49
	v_sub_u32_e32 v9, v49, v9
	s_movk_i32 s1, 0xff7e
	v_mul_lo_u32 v1, v51, s0
	v_mul_lo_u32 v2, v56, s0
	v_mul_lo_u32 v3, v57, s0
	v_mul_lo_u32 v4, v58, s0
	v_mul_lo_u32 v5, v59, s0
	v_mul_lo_u32 v6, v60, s0
	v_mul_lo_u32 v7, v61, s0
	v_mul_lo_u32 v8, v62, s0
	s_movk_i32 s0, 0x81
	v_cmp_lt_u32_e64 s[40:41], s1, v9
	v_sub_u32_e32 v9, v154, v49
	v_cmp_gt_u32_e64 s[38:39], s0, v10
	v_add_u32_e32 v10, 0x7e, v9
	v_cmp_gt_u32_e64 s[42:43], s0, v10
	v_add_u32_e32 v10, 0x7d, v9
	v_cmp_gt_u32_e64 s[44:45], s0, v10
	v_sub_u32_e32 v10, v49, v154
	v_cmp_gt_u32_e64 s[46:47], s0, v9
	v_cmp_lt_u32_e64 s[48:49], s1, v10
	v_add_u32_e32 v10, -2, v9
	v_add_u32_e32 v9, -3, v9
	v_cmp_gt_u32_e64 s[52:53], s0, v9
	v_lshrrev_b32_e32 v9, 2, v154
	v_or_b32_e32 v63, v49, v9
	v_lshlrev_b32_e32 v9, 3, v212
	v_lshl_add_u32 v0, v154, 4, 0
	v_and_b32_e32 v9, 24, v9
	v_lshlrev_b32_e32 v48, 3, v154
	v_cmp_gt_u32_e64 s[50:51], s0, v10
	v_cmp_gt_u32_e64 s[54:55], 16, v182
	v_or_b32_e32 v64, 16, v63
	v_add_u32_e32 v50, 0, v9
	s_waitcnt vmcnt(0)
	v_add_u32_e32 v65, v0, v1
	v_add_u32_e32 v66, v0, v2
	v_add_u32_e32 v67, v0, v3
	v_add_u32_e32 v68, v0, v4
	v_add_u32_e32 v69, v0, v5
	v_add_u32_e32 v70, v0, v6
	v_add_u32_e32 v71, v0, v7
	v_add_u32_e32 v72, v0, v8
	v_readlane_b32 s8, v251, 0
	s_branch .LBB0_197

; #define LAS __attribute__((address_space(3)))
; __global__ void __launch_bounds__(NTHREADS, 2) mega(Args a) {
;     extern __shared__ __attribute__((aligned(16))) unsigned char lds_raw[];
;     LAS unsigned char* lds = (LAS unsigned char*)lds_raw;
	.amdhsa_kernel _Z4mega4Args
		.amdhsa_group_segment_fixed_size 0
		.amdhsa_private_segment_fixed_size 0
		.amdhsa_kernarg_size 424
		.amdhsa_user_sgpr_count 2
		.amdhsa_user_sgpr_dispatch_ptr 0
		.amdhsa_user_sgpr_queue_ptr 0
		.amdhsa_user_sgpr_kernarg_segment_ptr 1
		.amdhsa_user_sgpr_dispatch_id 0
		.amdhsa_user_sgpr_kernarg_preload_length 0
		.amdhsa_user_sgpr_kernarg_preload_offset 0
		.amdhsa_user_sgpr_private_segment_size 0
		.amdhsa_uses_dynamic_stack 0
		.amdhsa_enable_private_segment 0
		.amdhsa_system_sgpr_workgroup_id_x 1
		.amdhsa_system_sgpr_workgroup_id_y 0
		.amdhsa_system_sgpr_workgroup_id_z 0
		.amdhsa_system_sgpr_workgroup_info 0
		.amdhsa_system_vgpr_workitem_id 2
		.amdhsa_next_free_vgpr 255
		.amdhsa_next_free_sgpr 102
		.amdhsa_accum_offset 256
		.amdhsa_reserve_vcc 1
		.amdhsa_float_round_mode_32 0
		.amdhsa_float_round_mode_16_64 0
		.amdhsa_float_denorm_mode_32 3
		.amdhsa_float_denorm_mode_16_64 3
		.amdhsa_dx10_clamp 1
		.amdhsa_ieee_mode 1
		.amdhsa_fp16_overflow 0
		.amdhsa_tg_split 0
		.amdhsa_exception_fp_ieee_invalid_op 0
		.amdhsa_exception_fp_denorm_src 0
		.amdhsa_exception_fp_ieee_div_zero 0
		.amdhsa_exception_fp_ieee_overflow 0
		.amdhsa_exception_fp_ieee_underflow 0
		.amdhsa_exception_fp_ieee_inexact 0
		.amdhsa_exception_int_div_zero 0
	.end_amdhsa_kernel

; #define LAS __attribute__((address_space(3)))
; __global__ void __launch_bounds__(NTHREADS, 2) mega(Args a) {
;     extern __shared__ __attribute__((aligned(16))) unsigned char lds_raw[];
;     LAS unsigned char* lds = (LAS unsigned char*)lds_raw;
amdhsa.kernels:
  - .agpr_count:     0
    .args:
      - .offset:         0
        .size:           168
        .value_kind:     by_value
      - .offset:         168
        .size:           4
        .value_kind:     hidden_block_count_x
      - .offset:         172
        .size:           4
        .value_kind:     hidden_block_count_y
      - .offset:         176
        .size:           4
        .value_kind:     hidden_block_count_z
      - .offset:         180
        .size:           2
        .value_kind:     hidden_group_size_x
      - .offset:         182
        .size:           2
        .value_kind:     hidden_group_size_y
      - .offset:         184
        .size:           2
        .value_kind:     hidden_group_size_z
      - .offset:         186
        .size:           2
        .value_kind:     hidden_remainder_x
      - .offset:         188
        .size:           2
        .value_kind:     hidden_remainder_y
      - .offset:         190
        .size:           2
        .value_kind:     hidden_remainder_z
      - .offset:         208
        .size:           8
        .value_kind:     hidden_global_offset_x
      - .offset:         216
        .size:           8
        .value_kind:     hidden_global_offset_y
      - .offset:         224
        .size:           8
        .value_kind:     hidden_global_offset_z
      - .offset:         232
        .size:           2
        .value_kind:     hidden_grid_dims
      - .offset:         256
        .size:           8
        .value_kind:     hidden_multigrid_sync_arg
      - .offset:         288
        .size:           4
        .value_kind:     hidden_dynamic_lds_size
    .group_segment_fixed_size: 0
    .kernarg_segment_align: 8
    .kernarg_segment_size: 424
    .language:       OpenCL C
    .language_version:
      - 2
      - 0
    .max_flat_workgroup_size: 512
    .name:           _Z4mega4Args
    .private_segment_fixed_size: 0
    .sgpr_count:     108
    .sgpr_spill_count: 302
    .symbol:         _Z4mega4Args.kd
    .uniform_work_group_size: 1
    .uses_dynamic_stack: false
    .vgpr_count:     255
    .vgpr_spill_count: 0
    .wavefront_size: 64
